# hand-written weight transpose/convert jobs in P0/P15 for the 256-WG grid: 3 tile loads in flight, 3 LDS buffers, one barrier per tile (compiled loops kept as fallback for other grids)
# baseline (speedup 1.0000x reference)
.LBB0_17:
	v_readlane_b32 s0, v254, 0
	v_readlane_b32 s1, v254, 1
	s_load_dword s80, s[0:1], 0xf0
	s_cmp_gt_i32 s42, 0
	s_cselect_b64 s[0:1], -1, 0
	s_cmp_lt_i32 s43, 1
	s_cselect_b64 s[2:3], -1, 0
	s_or_b64 s[0:1], s[0:1], s[2:3]
	s_and_b64 vcc, exec, s[0:1]
	s_cbranch_vccnz .LBB0_129
	s_waitcnt lgkmcnt(0)
	s_cmpk_lg_i32 s80, 0x100
	s_cbranch_scc1 .Lcv_skip_P0
	v_mbcnt_lo_u32_b32 v100, -1, 0
	v_mbcnt_hi_u32_b32 v100, -1, v100
	v_readlane_b32 s98, v254, 2
	s_nop 2
	v_lshl_add_u32 v100, s98, 6, v100
	v_lshrrev_b32_e32 v101, 3, v100
	v_and_b32_e32 v102, 7, v100
	v_lshlrev_b32_e32 v102, 2, v102
	v_lshrrev_b32_e32 v103, 4, v100
	v_and_b32_e32 v104, 15, v100
	v_lshlrev_b32_e32 v104, 2, v104
	v_mul_u32_u24_e32 v105, 33, v101
	v_add_u32_e32 v105, v105, v102
	v_lshlrev_b32_e32 v105, 2, v105
	v_add_u32_e32 v106, 0x2100, v105
	v_add_u32_e32 v107, 0x4200, v105
	v_mul_u32_u24_e32 v132, 33, v104
	v_add_u32_e32 v132, v132, v103
	v_lshlrev_b32_e32 v132, 2, v132
	v_add_u32_e32 v133, 0x2100, v132
	v_add_u32_e32 v134, 0x4200, v132
	v_mov_b32_e32 v109, 0
	v_mov_b32_e32 v113, 0
	s_cmp_lt_u32 s82, 0x690
	s_cbranch_scc0 .Lcv_none_P0_winrw
	v_readlane_b32 s98, v254, 0
	v_readlane_b32 s99, v254, 1
	s_load_dwordx2 s[100:101], s[98:99], 0x28
	s_load_dwordx2 s[98:99], s[98:99], 0xe0
	v_mul_u32_u24_e32 v108, 0x9c80, v101
	v_lshl_add_u32 v108, v102, 2, v108
	v_add_u32_e32 v108, 0x4800, v108
	v_mul_u32_u24_e32 v112, 0x800, v103
	v_lshl_add_u32 v112, v104, 1, v112
	s_waitcnt lgkmcnt(0)
	v_lshl_add_u64 v[110:111], s[100:101], 0, v[108:109]
	s_add_u32 s98, s98, 0x800000
	s_addc_u32 s99, s99, 0
	v_lshl_add_u64 v[114:115], s[98:99], 0, v[112:113]
	s_mov_b32 s101, 0
	s_mov_b32 s98, s82
	s_mov_b32 s99, s98
	s_lshr_b32 s100, s99, 4
	s_and_b32 s99, s99, 15
	s_mul_i32 s100, s100, 0x80
	s_mul_i32 s99, s99, 0x272000
	s_add_u32 s100, s100, s99
	v_lshl_add_u64 v[118:119], s[100:101], 0, v[110:111]
	global_load_dwordx4 v[124:127], v[118:119], off
	s_add_u32 s99, s98, 0x100
	s_min_u32 s99, s99, 0x68f
	s_lshr_b32 s100, s99, 4
	s_and_b32 s99, s99, 15
	s_mul_i32 s100, s100, 0x80
	s_mul_i32 s99, s99, 0x272000
	s_add_u32 s100, s100, s99
	v_lshl_add_u64 v[118:119], s[100:101], 0, v[110:111]
	global_load_dwordx4 v[128:131], v[118:119], off
	s_add_u32 s99, s98, 0x200
	s_min_u32 s99, s99, 0x68f
	s_lshr_b32 s100, s99, 4
	s_and_b32 s99, s99, 15
	s_mul_i32 s100, s100, 0x80
	s_mul_i32 s99, s99, 0x272000
	s_add_u32 s100, s100, s99
	v_lshl_add_u64 v[118:119], s[100:101], 0, v[110:111]
	global_load_dwordx4 v[136:139], v[118:119], off
	s_waitcnt vmcnt(2)
	ds_write2_b32 v105, v124, v125 offset1:1
	ds_write2_b32 v105, v126, v127 offset0:2 offset1:3
	s_mov_b32 s99, s98
	s_lshr_b32 s100, s99, 4
	s_and_b32 s99, s99, 15
	s_mul_i32 s100, s100, 0x10000
	s_mul_i32 s99, s99, 0x80
	s_add_u32 s100, s100, s99
	v_lshl_add_u64 v[116:117], s[100:101], 0, v[114:115]
	s_waitcnt lgkmcnt(0)
	s_barrier
	ds_read2_b32 v[120:121], v132 offset1:33
	ds_read2_b32 v[122:123], v132 offset0:66 offset1:99
	s_add_u32 s99, s98, 0x300
	s_min_u32 s99, s99, 0x68f
	s_lshr_b32 s100, s99, 4
	s_and_b32 s99, s99, 15
	s_mul_i32 s100, s100, 0x80
	s_mul_i32 s99, s99, 0x272000
	s_add_u32 s100, s100, s99
	v_lshl_add_u64 v[118:119], s[100:101], 0, v[110:111]
	global_load_dwordx4 v[124:127], v[118:119], off
	s_waitcnt lgkmcnt(0)
	v_cvt_pk_bf16_f32 v120, v120, v121
	v_cvt_pk_bf16_f32 v121, v122, v123
	global_store_dwordx2 v[116:117], v[120:121], off
	s_add_u32 s98, s98, 0x100
	s_cmp_lt_u32 s98, 0x690
	s_cbranch_scc0 .Lcv_done_P0_winrw
	s_waitcnt vmcnt(3)
	ds_write2_b32 v106, v128, v129 offset1:1
	ds_write2_b32 v106, v130, v131 offset0:2 offset1:3
	s_mov_b32 s99, s98
	s_lshr_b32 s100, s99, 4
	s_and_b32 s99, s99, 15
	s_mul_i32 s100, s100, 0x10000
	s_mul_i32 s99, s99, 0x80
	s_add_u32 s100, s100, s99
	v_lshl_add_u64 v[116:117], s[100:101], 0, v[114:115]
	s_waitcnt lgkmcnt(0)
	s_barrier
	ds_read2_b32 v[120:121], v133 offset1:33
	ds_read2_b32 v[122:123], v133 offset0:66 offset1:99
	s_add_u32 s99, s98, 0x300
	s_min_u32 s99, s99, 0x68f
	s_lshr_b32 s100, s99, 4
	s_and_b32 s99, s99, 15
	s_mul_i32 s100, s100, 0x80
	s_mul_i32 s99, s99, 0x272000
	s_add_u32 s100, s100, s99
	v_lshl_add_u64 v[118:119], s[100:101], 0, v[110:111]
	global_load_dwordx4 v[128:131], v[118:119], off
	s_waitcnt lgkmcnt(0)
	v_cvt_pk_bf16_f32 v120, v120, v121
	v_cvt_pk_bf16_f32 v121, v122, v123
	global_store_dwordx2 v[116:117], v[120:121], off
	s_add_u32 s98, s98, 0x100
	s_cmp_lt_u32 s98, 0x690
	s_cbranch_scc0 .Lcv_done_P0_winrw
	s_waitcnt vmcnt(4)
	ds_write2_b32 v107, v136, v137 offset1:1
	ds_write2_b32 v107, v138, v139 offset0:2 offset1:3
	s_mov_b32 s99, s98
	s_lshr_b32 s100, s99, 4
	s_and_b32 s99, s99, 15
	s_mul_i32 s100, s100, 0x10000
	s_mul_i32 s99, s99, 0x80
	s_add_u32 s100, s100, s99
	v_lshl_add_u64 v[116:117], s[100:101], 0, v[114:115]
	s_waitcnt lgkmcnt(0)
	s_barrier
	ds_read2_b32 v[120:121], v134 offset1:33
	ds_read2_b32 v[122:123], v134 offset0:66 offset1:99
	s_add_u32 s99, s98, 0x300
	s_min_u32 s99, s99, 0x68f
	s_lshr_b32 s100, s99, 4
	s_and_b32 s99, s99, 15
	s_mul_i32 s100, s100, 0x80
	s_mul_i32 s99, s99, 0x272000
	s_add_u32 s100, s100, s99
	v_lshl_add_u64 v[118:119], s[100:101], 0, v[110:111]
	global_load_dwordx4 v[136:139], v[118:119], off
	s_waitcnt lgkmcnt(0)
	v_cvt_pk_bf16_f32 v120, v120, v121
	v_cvt_pk_bf16_f32 v121, v122, v123
	global_store_dwordx2 v[116:117], v[120:121], off
	s_add_u32 s98, s98, 0x100
	s_cmp_lt_u32 s98, 0x690
	s_cbranch_scc0 .Lcv_done_P0_winrw
.Lcv_loop_P0_winrw:
	s_waitcnt vmcnt(5)
	ds_write2_b32 v105, v124, v125 offset1:1
	ds_write2_b32 v105, v126, v127 offset0:2 offset1:3
	s_mov_b32 s99, s98
	s_lshr_b32 s100, s99, 4
	s_and_b32 s99, s99, 15
	s_mul_i32 s100, s100, 0x10000
	s_mul_i32 s99, s99, 0x80
	s_add_u32 s100, s100, s99
	v_lshl_add_u64 v[116:117], s[100:101], 0, v[114:115]
	s_waitcnt lgkmcnt(0)
	s_barrier
	ds_read2_b32 v[120:121], v132 offset1:33
	ds_read2_b32 v[122:123], v132 offset0:66 offset1:99
	s_add_u32 s99, s98, 0x300
	s_min_u32 s99, s99, 0x68f
	s_lshr_b32 s100, s99, 4
	s_and_b32 s99, s99, 15
	s_mul_i32 s100, s100, 0x80
	s_mul_i32 s99, s99, 0x272000
	s_add_u32 s100, s100, s99
	v_lshl_add_u64 v[118:119], s[100:101], 0, v[110:111]
	global_load_dwordx4 v[124:127], v[118:119], off
	s_waitcnt lgkmcnt(0)
	v_cvt_pk_bf16_f32 v120, v120, v121
	v_cvt_pk_bf16_f32 v121, v122, v123
	global_store_dwordx2 v[116:117], v[120:121], off
	s_add_u32 s98, s98, 0x100
	s_cmp_lt_u32 s98, 0x690
	s_cbranch_scc0 .Lcv_done_P0_winrw
	s_waitcnt vmcnt(5)
	ds_write2_b32 v106, v128, v129 offset1:1
	ds_write2_b32 v106, v130, v131 offset0:2 offset1:3
	s_mov_b32 s99, s98
	s_lshr_b32 s100, s99, 4
	s_and_b32 s99, s99, 15
	s_mul_i32 s100, s100, 0x10000
	s_mul_i32 s99, s99, 0x80
	s_add_u32 s100, s100, s99
	v_lshl_add_u64 v[116:117], s[100:101], 0, v[114:115]
	s_waitcnt lgkmcnt(0)
	s_barrier
	ds_read2_b32 v[120:121], v133 offset1:33
	ds_read2_b32 v[122:123], v133 offset0:66 offset1:99
	s_add_u32 s99, s98, 0x300
	s_min_u32 s99, s99, 0x68f
	s_lshr_b32 s100, s99, 4
	s_and_b32 s99, s99, 15
	s_mul_i32 s100, s100, 0x80
	s_mul_i32 s99, s99, 0x272000
	s_add_u32 s100, s100, s99
	v_lshl_add_u64 v[118:119], s[100:101], 0, v[110:111]
	global_load_dwordx4 v[128:131], v[118:119], off
	s_waitcnt lgkmcnt(0)
	v_cvt_pk_bf16_f32 v120, v120, v121
	v_cvt_pk_bf16_f32 v121, v122, v123
	global_store_dwordx2 v[116:117], v[120:121], off
	s_add_u32 s98, s98, 0x100
	s_cmp_lt_u32 s98, 0x690
	s_cbranch_scc0 .Lcv_done_P0_winrw
	s_waitcnt vmcnt(5)
	ds_write2_b32 v107, v136, v137 offset1:1
	ds_write2_b32 v107, v138, v139 offset0:2 offset1:3
	s_mov_b32 s99, s98
	s_lshr_b32 s100, s99, 4
	s_and_b32 s99, s99, 15
	s_mul_i32 s100, s100, 0x10000
	s_mul_i32 s99, s99, 0x80
	s_add_u32 s100, s100, s99
	v_lshl_add_u64 v[116:117], s[100:101], 0, v[114:115]
	s_waitcnt lgkmcnt(0)
	s_barrier
	ds_read2_b32 v[120:121], v134 offset1:33
	ds_read2_b32 v[122:123], v134 offset0:66 offset1:99
	s_add_u32 s99, s98, 0x300
	s_min_u32 s99, s99, 0x68f
	s_lshr_b32 s100, s99, 4
	s_and_b32 s99, s99, 15
	s_mul_i32 s100, s100, 0x80
	s_mul_i32 s99, s99, 0x272000
	s_add_u32 s100, s100, s99
	v_lshl_add_u64 v[118:119], s[100:101], 0, v[110:111]
	global_load_dwordx4 v[136:139], v[118:119], off
	s_waitcnt lgkmcnt(0)
	v_cvt_pk_bf16_f32 v120, v120, v121
	v_cvt_pk_bf16_f32 v121, v122, v123
	global_store_dwordx2 v[116:117], v[120:121], off
	s_add_u32 s98, s98, 0x100
	s_cmp_lt_u32 s98, 0x690
	s_cbranch_scc0 .Lcv_done_P0_winrw
	s_branch .Lcv_loop_P0_winrw
.Lcv_done_P0_winrw:
	s_barrier
.Lcv_none_P0_winrw:
	s_cmp_lt_u32 s82, 0x900
	s_cbranch_scc0 .Lcv_none_P0_winag0
	v_readlane_b32 s98, v254, 0
	v_readlane_b32 s99, v254, 1
	s_load_dwordx2 s[100:101], s[98:99], 0x28
	s_load_dwordx2 s[98:99], s[98:99], 0xe0
	v_mul_u32_u24_e32 v108, 0x9c80, v101
	v_lshl_add_u32 v108, v102, 2, v108
	v_mul_u32_u24_e32 v112, 0x800, v103
	v_lshl_add_u32 v112, v104, 1, v112
	s_waitcnt lgkmcnt(0)
	v_lshl_add_u64 v[110:111], s[100:101], 0, v[108:109]
	s_add_u32 s98, s98, 0xf00000
	s_addc_u32 s99, s99, 0
	v_lshl_add_u64 v[114:115], s[98:99], 0, v[112:113]
	s_mov_b32 s101, 0
	s_mov_b32 s98, s82
	s_mov_b32 s99, s98
	s_lshr_b32 s100, s99, 4
	s_and_b32 s99, s99, 15
	s_mul_i32 s100, s100, 0x80
	s_mul_i32 s99, s99, 0x272000
	s_add_u32 s100, s100, s99
	v_lshl_add_u64 v[118:119], s[100:101], 0, v[110:111]
	global_load_dwordx4 v[124:127], v[118:119], off
	s_add_u32 s99, s98, 0x100
	s_min_u32 s99, s99, 0x8ff
	s_lshr_b32 s100, s99, 4
	s_and_b32 s99, s99, 15
	s_mul_i32 s100, s100, 0x80
	s_mul_i32 s99, s99, 0x272000
	s_add_u32 s100, s100, s99
	v_lshl_add_u64 v[118:119], s[100:101], 0, v[110:111]
	global_load_dwordx4 v[128:131], v[118:119], off
	s_add_u32 s99, s98, 0x200
	s_min_u32 s99, s99, 0x8ff
	s_lshr_b32 s100, s99, 4
	s_and_b32 s99, s99, 15
	s_mul_i32 s100, s100, 0x80
	s_mul_i32 s99, s99, 0x272000
	s_add_u32 s100, s100, s99
	v_lshl_add_u64 v[118:119], s[100:101], 0, v[110:111]
	global_load_dwordx4 v[136:139], v[118:119], off
	s_waitcnt vmcnt(2)
	ds_write2_b32 v105, v124, v125 offset1:1
	ds_write2_b32 v105, v126, v127 offset0:2 offset1:3
	s_mov_b32 s99, s98
	s_lshr_b32 s100, s99, 4
	s_and_b32 s99, s99, 15
	s_mul_i32 s100, s100, 0x10000
	s_mul_i32 s99, s99, 0x80
	s_add_u32 s100, s100, s99
	v_lshl_add_u64 v[116:117], s[100:101], 0, v[114:115]
	s_waitcnt lgkmcnt(0)
	s_barrier
	ds_read2_b32 v[120:121], v132 offset1:33
	ds_read2_b32 v[122:123], v132 offset0:66 offset1:99
	s_add_u32 s99, s98, 0x300
	s_min_u32 s99, s99, 0x8ff
	s_lshr_b32 s100, s99, 4
	s_and_b32 s99, s99, 15
	s_mul_i32 s100, s100, 0x80
	s_mul_i32 s99, s99, 0x272000
	s_add_u32 s100, s100, s99
	v_lshl_add_u64 v[118:119], s[100:101], 0, v[110:111]
	global_load_dwordx4 v[124:127], v[118:119], off
	s_waitcnt lgkmcnt(0)
	v_cvt_pk_bf16_f32 v120, v120, v121
	v_cvt_pk_bf16_f32 v121, v122, v123
	global_store_dwordx2 v[116:117], v[120:121], off
	s_add_u32 s98, s98, 0x100
	s_cmp_lt_u32 s98, 0x900
	s_cbranch_scc0 .Lcv_done_P0_winag0
	s_waitcnt vmcnt(3)
	ds_write2_b32 v106, v128, v129 offset1:1
	ds_write2_b32 v106, v130, v131 offset0:2 offset1:3
	s_mov_b32 s99, s98
	s_lshr_b32 s100, s99, 4
	s_and_b32 s99, s99, 15
	s_mul_i32 s100, s100, 0x10000
	s_mul_i32 s99, s99, 0x80
	s_add_u32 s100, s100, s99
	v_lshl_add_u64 v[116:117], s[100:101], 0, v[114:115]
	s_waitcnt lgkmcnt(0)
	s_barrier
	ds_read2_b32 v[120:121], v133 offset1:33
	ds_read2_b32 v[122:123], v133 offset0:66 offset1:99
	s_add_u32 s99, s98, 0x300
	s_min_u32 s99, s99, 0x8ff
	s_lshr_b32 s100, s99, 4
	s_and_b32 s99, s99, 15
	s_mul_i32 s100, s100, 0x80
	s_mul_i32 s99, s99, 0x272000
	s_add_u32 s100, s100, s99
	v_lshl_add_u64 v[118:119], s[100:101], 0, v[110:111]
	global_load_dwordx4 v[128:131], v[118:119], off
	s_waitcnt lgkmcnt(0)
	v_cvt_pk_bf16_f32 v120, v120, v121
	v_cvt_pk_bf16_f32 v121, v122, v123
	global_store_dwordx2 v[116:117], v[120:121], off
	s_add_u32 s98, s98, 0x100
	s_cmp_lt_u32 s98, 0x900
	s_cbranch_scc0 .Lcv_done_P0_winag0
	s_waitcnt vmcnt(4)
	ds_write2_b32 v107, v136, v137 offset1:1
	ds_write2_b32 v107, v138, v139 offset0:2 offset1:3
	s_mov_b32 s99, s98
	s_lshr_b32 s100, s99, 4
	s_and_b32 s99, s99, 15
	s_mul_i32 s100, s100, 0x10000
	s_mul_i32 s99, s99, 0x80
	s_add_u32 s100, s100, s99
	v_lshl_add_u64 v[116:117], s[100:101], 0, v[114:115]
	s_waitcnt lgkmcnt(0)
	s_barrier
	ds_read2_b32 v[120:121], v134 offset1:33
	ds_read2_b32 v[122:123], v134 offset0:66 offset1:99
	s_add_u32 s99, s98, 0x300
	s_min_u32 s99, s99, 0x8ff
	s_lshr_b32 s100, s99, 4
	s_and_b32 s99, s99, 15
	s_mul_i32 s100, s100, 0x80
	s_mul_i32 s99, s99, 0x272000
	s_add_u32 s100, s100, s99
	v_lshl_add_u64 v[118:119], s[100:101], 0, v[110:111]
	global_load_dwordx4 v[136:139], v[118:119], off
	s_waitcnt lgkmcnt(0)
	v_cvt_pk_bf16_f32 v120, v120, v121
	v_cvt_pk_bf16_f32 v121, v122, v123
	global_store_dwordx2 v[116:117], v[120:121], off
	s_add_u32 s98, s98, 0x100
	s_cmp_lt_u32 s98, 0x900
	s_cbranch_scc0 .Lcv_done_P0_winag0
.Lcv_loop_P0_winag0:
	s_waitcnt vmcnt(5)
	ds_write2_b32 v105, v124, v125 offset1:1
	ds_write2_b32 v105, v126, v127 offset0:2 offset1:3
	s_mov_b32 s99, s98
	s_lshr_b32 s100, s99, 4
	s_and_b32 s99, s99, 15
	s_mul_i32 s100, s100, 0x10000
	s_mul_i32 s99, s99, 0x80
	s_add_u32 s100, s100, s99
	v_lshl_add_u64 v[116:117], s[100:101], 0, v[114:115]
	s_waitcnt lgkmcnt(0)
	s_barrier
	ds_read2_b32 v[120:121], v132 offset1:33
	ds_read2_b32 v[122:123], v132 offset0:66 offset1:99
	s_add_u32 s99, s98, 0x300
	s_min_u32 s99, s99, 0x8ff
	s_lshr_b32 s100, s99, 4
	s_and_b32 s99, s99, 15
	s_mul_i32 s100, s100, 0x80
	s_mul_i32 s99, s99, 0x272000
	s_add_u32 s100, s100, s99
	v_lshl_add_u64 v[118:119], s[100:101], 0, v[110:111]
	global_load_dwordx4 v[124:127], v[118:119], off
	s_waitcnt lgkmcnt(0)
	v_cvt_pk_bf16_f32 v120, v120, v121
	v_cvt_pk_bf16_f32 v121, v122, v123
	global_store_dwordx2 v[116:117], v[120:121], off
	s_add_u32 s98, s98, 0x100
	s_cmp_lt_u32 s98, 0x900
	s_cbranch_scc0 .Lcv_done_P0_winag0
	s_waitcnt vmcnt(5)
	ds_write2_b32 v106, v128, v129 offset1:1
	ds_write2_b32 v106, v130, v131 offset0:2 offset1:3
	s_mov_b32 s99, s98
	s_lshr_b32 s100, s99, 4
	s_and_b32 s99, s99, 15
	s_mul_i32 s100, s100, 0x10000
	s_mul_i32 s99, s99, 0x80
	s_add_u32 s100, s100, s99
	v_lshl_add_u64 v[116:117], s[100:101], 0, v[114:115]
	s_waitcnt lgkmcnt(0)
	s_barrier
	ds_read2_b32 v[120:121], v133 offset1:33
	ds_read2_b32 v[122:123], v133 offset0:66 offset1:99
	s_add_u32 s99, s98, 0x300
	s_min_u32 s99, s99, 0x8ff
	s_lshr_b32 s100, s99, 4
	s_and_b32 s99, s99, 15
	s_mul_i32 s100, s100, 0x80
	s_mul_i32 s99, s99, 0x272000
	s_add_u32 s100, s100, s99
	v_lshl_add_u64 v[118:119], s[100:101], 0, v[110:111]
	global_load_dwordx4 v[128:131], v[118:119], off
	s_waitcnt lgkmcnt(0)
	v_cvt_pk_bf16_f32 v120, v120, v121
	v_cvt_pk_bf16_f32 v121, v122, v123
	global_store_dwordx2 v[116:117], v[120:121], off
	s_add_u32 s98, s98, 0x100
	s_cmp_lt_u32 s98, 0x900
	s_cbranch_scc0 .Lcv_done_P0_winag0
	s_waitcnt vmcnt(5)
	ds_write2_b32 v107, v136, v137 offset1:1
	ds_write2_b32 v107, v138, v139 offset0:2 offset1:3
	s_mov_b32 s99, s98
	s_lshr_b32 s100, s99, 4
	s_and_b32 s99, s99, 15
	s_mul_i32 s100, s100, 0x10000
	s_mul_i32 s99, s99, 0x80
	s_add_u32 s100, s100, s99
	v_lshl_add_u64 v[116:117], s[100:101], 0, v[114:115]
	s_waitcnt lgkmcnt(0)
	s_barrier
	ds_read2_b32 v[120:121], v134 offset1:33
	ds_read2_b32 v[122:123], v134 offset0:66 offset1:99
	s_add_u32 s99, s98, 0x300
	s_min_u32 s99, s99, 0x8ff
	s_lshr_b32 s100, s99, 4
	s_and_b32 s99, s99, 15
	s_mul_i32 s100, s100, 0x80
	s_mul_i32 s99, s99, 0x272000
	s_add_u32 s100, s100, s99
	v_lshl_add_u64 v[118:119], s[100:101], 0, v[110:111]
	global_load_dwordx4 v[136:139], v[118:119], off
	s_waitcnt lgkmcnt(0)
	v_cvt_pk_bf16_f32 v120, v120, v121
	v_cvt_pk_bf16_f32 v121, v122, v123
	global_store_dwordx2 v[116:117], v[120:121], off
	s_add_u32 s98, s98, 0x100
	s_cmp_lt_u32 s98, 0x900
	s_cbranch_scc0 .Lcv_done_P0_winag0
	s_branch .Lcv_loop_P0_winag0

.Lcv_none_P0_winag0:
	s_cmp_lt_u32 s82, 0x400
	s_cbranch_scc0 .Lcv_none_P0_winag1
	v_readlane_b32 s98, v254, 0
	v_readlane_b32 s99, v254, 1
	s_load_dwordx2 s[100:101], s[98:99], 0x28
	s_load_dwordx2 s[98:99], s[98:99], 0xe0
	v_mul_u32_u24_e32 v108, 0x9c80, v101
	v_lshl_add_u32 v108, v102, 2, v108
	v_add_u32_e32 v108, 0x7c80, v108
	v_mul_u32_u24_e32 v112, 0x800, v103
	v_lshl_add_u32 v112, v104, 1, v112
	v_add_u32_e32 v112, 0x900000, v112
	s_waitcnt lgkmcnt(0)
	v_lshl_add_u64 v[110:111], s[100:101], 0, v[108:109]
	s_add_u32 s98, s98, 0xf00000
	s_addc_u32 s99, s99, 0
	v_lshl_add_u64 v[114:115], s[98:99], 0, v[112:113]
	s_mov_b32 s101, 0
	s_mov_b32 s98, s82
	s_mov_b32 s99, s98
	s_lshr_b32 s100, s99, 4
	s_and_b32 s99, s99, 15
	s_mul_i32 s100, s100, 0x80
	s_mul_i32 s99, s99, 0x272000
	s_add_u32 s100, s100, s99
	v_lshl_add_u64 v[118:119], s[100:101], 0, v[110:111]
	global_load_dwordx4 v[124:127], v[118:119], off
	s_add_u32 s99, s98, 0x100
	s_min_u32 s99, s99, 0x3ff
	s_lshr_b32 s100, s99, 4
	s_and_b32 s99, s99, 15
	s_mul_i32 s100, s100, 0x80
	s_mul_i32 s99, s99, 0x272000
	s_add_u32 s100, s100, s99
	v_lshl_add_u64 v[118:119], s[100:101], 0, v[110:111]
	global_load_dwordx4 v[128:131], v[118:119], off
	s_add_u32 s99, s98, 0x200
	s_min_u32 s99, s99, 0x3ff
	s_lshr_b32 s100, s99, 4
	s_and_b32 s99, s99, 15
	s_mul_i32 s100, s100, 0x80
	s_mul_i32 s99, s99, 0x272000
	s_add_u32 s100, s100, s99
	v_lshl_add_u64 v[118:119], s[100:101], 0, v[110:111]
	global_load_dwordx4 v[136:139], v[118:119], off
	s_waitcnt vmcnt(2)
	ds_write2_b32 v105, v124, v125 offset1:1
	ds_write2_b32 v105, v126, v127 offset0:2 offset1:3
	s_mov_b32 s99, s98
	s_lshr_b32 s100, s99, 4
	s_and_b32 s99, s99, 15
	s_mul_i32 s100, s100, 0x10000
	s_mul_i32 s99, s99, 0x80
	s_add_u32 s100, s100, s99
	v_lshl_add_u64 v[116:117], s[100:101], 0, v[114:115]
	s_waitcnt lgkmcnt(0)
	s_barrier
	ds_read2_b32 v[120:121], v132 offset1:33
	ds_read2_b32 v[122:123], v132 offset0:66 offset1:99
	s_add_u32 s99, s98, 0x300
	s_min_u32 s99, s99, 0x3ff
	s_lshr_b32 s100, s99, 4
	s_and_b32 s99, s99, 15
	s_mul_i32 s100, s100, 0x80
	s_mul_i32 s99, s99, 0x272000
	s_add_u32 s100, s100, s99
	v_lshl_add_u64 v[118:119], s[100:101], 0, v[110:111]
	global_load_dwordx4 v[124:127], v[118:119], off
	s_waitcnt lgkmcnt(0)
	v_cvt_pk_bf16_f32 v120, v120, v121
	v_cvt_pk_bf16_f32 v121, v122, v123
	global_store_dwordx2 v[116:117], v[120:121], off
	s_add_u32 s98, s98, 0x100
	s_cmp_lt_u32 s98, 0x400
	s_cbranch_scc0 .Lcv_done_P0_winag1
	s_waitcnt vmcnt(3)
	ds_write2_b32 v106, v128, v129 offset1:1
	ds_write2_b32 v106, v130, v131 offset0:2 offset1:3
	s_mov_b32 s99, s98
	s_lshr_b32 s100, s99, 4
	s_and_b32 s99, s99, 15
	s_mul_i32 s100, s100, 0x10000
	s_mul_i32 s99, s99, 0x80
	s_add_u32 s100, s100, s99
	v_lshl_add_u64 v[116:117], s[100:101], 0, v[114:115]
	s_waitcnt lgkmcnt(0)
	s_barrier
	ds_read2_b32 v[120:121], v133 offset1:33
	ds_read2_b32 v[122:123], v133 offset0:66 offset1:99
	s_add_u32 s99, s98, 0x300
	s_min_u32 s99, s99, 0x3ff
	s_lshr_b32 s100, s99, 4
	s_and_b32 s99, s99, 15
	s_mul_i32 s100, s100, 0x80
	s_mul_i32 s99, s99, 0x272000
	s_add_u32 s100, s100, s99
	v_lshl_add_u64 v[118:119], s[100:101], 0, v[110:111]
	global_load_dwordx4 v[128:131], v[118:119], off
	s_waitcnt lgkmcnt(0)
	v_cvt_pk_bf16_f32 v120, v120, v121
	v_cvt_pk_bf16_f32 v121, v122, v123
	global_store_dwordx2 v[116:117], v[120:121], off
	s_add_u32 s98, s98, 0x100
	s_cmp_lt_u32 s98, 0x400
	s_cbranch_scc0 .Lcv_done_P0_winag1
	s_waitcnt vmcnt(4)
	ds_write2_b32 v107, v136, v137 offset1:1
	ds_write2_b32 v107, v138, v139 offset0:2 offset1:3
	s_mov_b32 s99, s98
	s_lshr_b32 s100, s99, 4
	s_and_b32 s99, s99, 15
	s_mul_i32 s100, s100, 0x10000
	s_mul_i32 s99, s99, 0x80
	s_add_u32 s100, s100, s99
	v_lshl_add_u64 v[116:117], s[100:101], 0, v[114:115]
	s_waitcnt lgkmcnt(0)
	s_barrier
	ds_read2_b32 v[120:121], v134 offset1:33
	ds_read2_b32 v[122:123], v134 offset0:66 offset1:99
	s_add_u32 s99, s98, 0x300
	s_min_u32 s99, s99, 0x3ff
	s_lshr_b32 s100, s99, 4
	s_and_b32 s99, s99, 15
	s_mul_i32 s100, s100, 0x80
	s_mul_i32 s99, s99, 0x272000
	s_add_u32 s100, s100, s99
	v_lshl_add_u64 v[118:119], s[100:101], 0, v[110:111]
	global_load_dwordx4 v[136:139], v[118:119], off
	s_waitcnt lgkmcnt(0)
	v_cvt_pk_bf16_f32 v120, v120, v121
	v_cvt_pk_bf16_f32 v121, v122, v123
	global_store_dwordx2 v[116:117], v[120:121], off
	s_add_u32 s98, s98, 0x100
	s_cmp_lt_u32 s98, 0x400
	s_cbranch_scc0 .Lcv_done_P0_winag1
.Lcv_loop_P0_winag1:
	s_waitcnt vmcnt(5)
	ds_write2_b32 v105, v124, v125 offset1:1
	ds_write2_b32 v105, v126, v127 offset0:2 offset1:3
	s_mov_b32 s99, s98
	s_lshr_b32 s100, s99, 4
	s_and_b32 s99, s99, 15
	s_mul_i32 s100, s100, 0x10000
	s_mul_i32 s99, s99, 0x80
	s_add_u32 s100, s100, s99
	v_lshl_add_u64 v[116:117], s[100:101], 0, v[114:115]
	s_waitcnt lgkmcnt(0)
	s_barrier
	ds_read2_b32 v[120:121], v132 offset1:33
	ds_read2_b32 v[122:123], v132 offset0:66 offset1:99
	s_add_u32 s99, s98, 0x300
	s_min_u32 s99, s99, 0x3ff
	s_lshr_b32 s100, s99, 4
	s_and_b32 s99, s99, 15
	s_mul_i32 s100, s100, 0x80
	s_mul_i32 s99, s99, 0x272000
	s_add_u32 s100, s100, s99
	v_lshl_add_u64 v[118:119], s[100:101], 0, v[110:111]
	global_load_dwordx4 v[124:127], v[118:119], off
	s_waitcnt lgkmcnt(0)
	v_cvt_pk_bf16_f32 v120, v120, v121
	v_cvt_pk_bf16_f32 v121, v122, v123
	global_store_dwordx2 v[116:117], v[120:121], off
	s_add_u32 s98, s98, 0x100
	s_cmp_lt_u32 s98, 0x400
	s_cbranch_scc0 .Lcv_done_P0_winag1
	s_waitcnt vmcnt(5)
	ds_write2_b32 v106, v128, v129 offset1:1
	ds_write2_b32 v106, v130, v131 offset0:2 offset1:3
	s_mov_b32 s99, s98
	s_lshr_b32 s100, s99, 4
	s_and_b32 s99, s99, 15
	s_mul_i32 s100, s100, 0x10000
	s_mul_i32 s99, s99, 0x80
	s_add_u32 s100, s100, s99
	v_lshl_add_u64 v[116:117], s[100:101], 0, v[114:115]
	s_waitcnt lgkmcnt(0)
	s_barrier
	ds_read2_b32 v[120:121], v133 offset1:33
	ds_read2_b32 v[122:123], v133 offset0:66 offset1:99
	s_add_u32 s99, s98, 0x300
	s_min_u32 s99, s99, 0x3ff
	s_lshr_b32 s100, s99, 4
	s_and_b32 s99, s99, 15
	s_mul_i32 s100, s100, 0x80
	s_mul_i32 s99, s99, 0x272000
	s_add_u32 s100, s100, s99
	v_lshl_add_u64 v[118:119], s[100:101], 0, v[110:111]
	global_load_dwordx4 v[128:131], v[118:119], off
	s_waitcnt lgkmcnt(0)
	v_cvt_pk_bf16_f32 v120, v120, v121
	v_cvt_pk_bf16_f32 v121, v122, v123
	global_store_dwordx2 v[116:117], v[120:121], off
	s_add_u32 s98, s98, 0x100
	s_cmp_lt_u32 s98, 0x400
	s_cbranch_scc0 .Lcv_done_P0_winag1
	s_waitcnt vmcnt(5)
	ds_write2_b32 v107, v136, v137 offset1:1
	ds_write2_b32 v107, v138, v139 offset0:2 offset1:3
	s_mov_b32 s99, s98
	s_lshr_b32 s100, s99, 4
	s_and_b32 s99, s99, 15
	s_mul_i32 s100, s100, 0x10000
	s_mul_i32 s99, s99, 0x80
	s_add_u32 s100, s100, s99
	v_lshl_add_u64 v[116:117], s[100:101], 0, v[114:115]
	s_waitcnt lgkmcnt(0)
	s_barrier
	ds_read2_b32 v[120:121], v134 offset1:33
	ds_read2_b32 v[122:123], v134 offset0:66 offset1:99
	s_add_u32 s99, s98, 0x300
	s_min_u32 s99, s99, 0x3ff
	s_lshr_b32 s100, s99, 4
	s_and_b32 s99, s99, 15
	s_mul_i32 s100, s100, 0x80
	s_mul_i32 s99, s99, 0x272000
	s_add_u32 s100, s100, s99
	v_lshl_add_u64 v[118:119], s[100:101], 0, v[110:111]
	global_load_dwordx4 v[136:139], v[118:119], off
	s_waitcnt lgkmcnt(0)
	v_cvt_pk_bf16_f32 v120, v120, v121
	v_cvt_pk_bf16_f32 v121, v122, v123
	global_store_dwordx2 v[116:117], v[120:121], off
	s_add_u32 s98, s98, 0x100
	s_cmp_lt_u32 s98, 0x400
	s_cbranch_scc0 .Lcv_done_P0_winag1
	s_branch .Lcv_loop_P0_winag1

.Lcv_none_P0_winag1:
	s_cmp_lt_u32 s82, 0x100
	s_cbranch_scc0 .Lcv_none_P0_watto
	v_readlane_b32 s98, v254, 0
	v_readlane_b32 s99, v254, 1
	s_load_dwordx2 s[100:101], s[98:99], 0x90
	s_load_dwordx2 s[98:99], s[98:99], 0xe0
	v_mul_u32_u24_e32 v108, 0x1000, v101
	v_lshl_add_u32 v108, v102, 2, v108
	v_mul_u32_u24_e32 v112, 0x400, v103
	v_lshl_add_u32 v112, v104, 1, v112
	s_waitcnt lgkmcnt(0)
	v_lshl_add_u64 v[110:111], s[100:101], 0, v[108:109]
	v_lshl_add_u64 v[114:115], s[98:99], 0, v[112:113]
	s_mov_b32 s101, 0
	s_mov_b32 s98, s82
	s_mov_b32 s99, s98
	s_lshr_b32 s100, s99, 3
	s_and_b32 s99, s99, 7
	s_mul_i32 s100, s100, 0x80
	s_mul_i32 s99, s99, 0x40000
	s_add_u32 s100, s100, s99
	v_lshl_add_u64 v[118:119], s[100:101], 0, v[110:111]
	global_load_dwordx4 v[124:127], v[118:119], off
	s_add_u32 s99, s98, 0x100
	s_min_u32 s99, s99, 0xff
	s_lshr_b32 s100, s99, 3
	s_and_b32 s99, s99, 7
	s_mul_i32 s100, s100, 0x80
	s_mul_i32 s99, s99, 0x40000
	s_add_u32 s100, s100, s99
	v_lshl_add_u64 v[118:119], s[100:101], 0, v[110:111]
	global_load_dwordx4 v[128:131], v[118:119], off
	s_add_u32 s99, s98, 0x200
	s_min_u32 s99, s99, 0xff
	s_lshr_b32 s100, s99, 3
	s_and_b32 s99, s99, 7
	s_mul_i32 s100, s100, 0x80
	s_mul_i32 s99, s99, 0x40000
	s_add_u32 s100, s100, s99
	v_lshl_add_u64 v[118:119], s[100:101], 0, v[110:111]
	global_load_dwordx4 v[136:139], v[118:119], off
	s_waitcnt vmcnt(2)
	ds_write2_b32 v105, v124, v125 offset1:1
	ds_write2_b32 v105, v126, v127 offset0:2 offset1:3
	s_mov_b32 s99, s98
	s_lshr_b32 s100, s99, 3
	s_and_b32 s99, s99, 7
	s_mul_i32 s100, s100, 0x8000
	s_mul_i32 s99, s99, 0x80
	s_add_u32 s100, s100, s99
	v_lshl_add_u64 v[116:117], s[100:101], 0, v[114:115]
	s_waitcnt lgkmcnt(0)
	s_barrier
	ds_read2_b32 v[120:121], v132 offset1:33
	ds_read2_b32 v[122:123], v132 offset0:66 offset1:99
	s_add_u32 s99, s98, 0x300
	s_min_u32 s99, s99, 0xff
	s_lshr_b32 s100, s99, 3
	s_and_b32 s99, s99, 7
	s_mul_i32 s100, s100, 0x80
	s_mul_i32 s99, s99, 0x40000
	s_add_u32 s100, s100, s99
	v_lshl_add_u64 v[118:119], s[100:101], 0, v[110:111]
	global_load_dwordx4 v[124:127], v[118:119], off
	s_waitcnt lgkmcnt(0)
	v_cvt_pk_bf16_f32 v120, v120, v121
	v_cvt_pk_bf16_f32 v121, v122, v123
	global_store_dwordx2 v[116:117], v[120:121], off
	s_add_u32 s98, s98, 0x100
	s_cmp_lt_u32 s98, 0x100
	s_cbranch_scc0 .Lcv_done_P0_watto
	s_waitcnt vmcnt(3)
	ds_write2_b32 v106, v128, v129 offset1:1
	ds_write2_b32 v106, v130, v131 offset0:2 offset1:3
	s_mov_b32 s99, s98
	s_lshr_b32 s100, s99, 3
	s_and_b32 s99, s99, 7
	s_mul_i32 s100, s100, 0x8000
	s_mul_i32 s99, s99, 0x80
	s_add_u32 s100, s100, s99
	v_lshl_add_u64 v[116:117], s[100:101], 0, v[114:115]
	s_waitcnt lgkmcnt(0)
	s_barrier
	ds_read2_b32 v[120:121], v133 offset1:33
	ds_read2_b32 v[122:123], v133 offset0:66 offset1:99
	s_add_u32 s99, s98, 0x300
	s_min_u32 s99, s99, 0xff
	s_lshr_b32 s100, s99, 3
	s_and_b32 s99, s99, 7
	s_mul_i32 s100, s100, 0x80
	s_mul_i32 s99, s99, 0x40000
	s_add_u32 s100, s100, s99
	v_lshl_add_u64 v[118:119], s[100:101], 0, v[110:111]
	global_load_dwordx4 v[128:131], v[118:119], off
	s_waitcnt lgkmcnt(0)
	v_cvt_pk_bf16_f32 v120, v120, v121
	v_cvt_pk_bf16_f32 v121, v122, v123
	global_store_dwordx2 v[116:117], v[120:121], off
	s_add_u32 s98, s98, 0x100
	s_cmp_lt_u32 s98, 0x100
	s_cbranch_scc0 .Lcv_done_P0_watto
	s_waitcnt vmcnt(4)
	ds_write2_b32 v107, v136, v137 offset1:1
	ds_write2_b32 v107, v138, v139 offset0:2 offset1:3
	s_mov_b32 s99, s98
	s_lshr_b32 s100, s99, 3
	s_and_b32 s99, s99, 7
	s_mul_i32 s100, s100, 0x8000
	s_mul_i32 s99, s99, 0x80
	s_add_u32 s100, s100, s99
	v_lshl_add_u64 v[116:117], s[100:101], 0, v[114:115]
	s_waitcnt lgkmcnt(0)
	s_barrier
	ds_read2_b32 v[120:121], v134 offset1:33
	ds_read2_b32 v[122:123], v134 offset0:66 offset1:99
	s_add_u32 s99, s98, 0x300
	s_min_u32 s99, s99, 0xff
	s_lshr_b32 s100, s99, 3
	s_and_b32 s99, s99, 7
	s_mul_i32 s100, s100, 0x80
	s_mul_i32 s99, s99, 0x40000
	s_add_u32 s100, s100, s99
	v_lshl_add_u64 v[118:119], s[100:101], 0, v[110:111]
	global_load_dwordx4 v[136:139], v[118:119], off
	s_waitcnt lgkmcnt(0)
	v_cvt_pk_bf16_f32 v120, v120, v121
	v_cvt_pk_bf16_f32 v121, v122, v123
	global_store_dwordx2 v[116:117], v[120:121], off
	s_add_u32 s98, s98, 0x100
	s_cmp_lt_u32 s98, 0x100
	s_cbranch_scc0 .Lcv_done_P0_watto
.Lcv_loop_P0_watto:
	s_waitcnt vmcnt(5)
	ds_write2_b32 v105, v124, v125 offset1:1
	ds_write2_b32 v105, v126, v127 offset0:2 offset1:3
	s_mov_b32 s99, s98
	s_lshr_b32 s100, s99, 3
	s_and_b32 s99, s99, 7
	s_mul_i32 s100, s100, 0x8000
	s_mul_i32 s99, s99, 0x80
	s_add_u32 s100, s100, s99
	v_lshl_add_u64 v[116:117], s[100:101], 0, v[114:115]
	s_waitcnt lgkmcnt(0)
	s_barrier
	ds_read2_b32 v[120:121], v132 offset1:33
	ds_read2_b32 v[122:123], v132 offset0:66 offset1:99
	s_add_u32 s99, s98, 0x300
	s_min_u32 s99, s99, 0xff
	s_lshr_b32 s100, s99, 3
	s_and_b32 s99, s99, 7
	s_mul_i32 s100, s100, 0x80
	s_mul_i32 s99, s99, 0x40000
	s_add_u32 s100, s100, s99
	v_lshl_add_u64 v[118:119], s[100:101], 0, v[110:111]
	global_load_dwordx4 v[124:127], v[118:119], off
	s_waitcnt lgkmcnt(0)
	v_cvt_pk_bf16_f32 v120, v120, v121
	v_cvt_pk_bf16_f32 v121, v122, v123
	global_store_dwordx2 v[116:117], v[120:121], off
	s_add_u32 s98, s98, 0x100
	s_cmp_lt_u32 s98, 0x100
	s_cbranch_scc0 .Lcv_done_P0_watto
	s_waitcnt vmcnt(5)
	ds_write2_b32 v106, v128, v129 offset1:1
	ds_write2_b32 v106, v130, v131 offset0:2 offset1:3
	s_mov_b32 s99, s98
	s_lshr_b32 s100, s99, 3
	s_and_b32 s99, s99, 7
	s_mul_i32 s100, s100, 0x8000
	s_mul_i32 s99, s99, 0x80
	s_add_u32 s100, s100, s99
	v_lshl_add_u64 v[116:117], s[100:101], 0, v[114:115]
	s_waitcnt lgkmcnt(0)
	s_barrier
	ds_read2_b32 v[120:121], v133 offset1:33
	ds_read2_b32 v[122:123], v133 offset0:66 offset1:99
	s_add_u32 s99, s98, 0x300
	s_min_u32 s99, s99, 0xff
	s_lshr_b32 s100, s99, 3
	s_and_b32 s99, s99, 7
	s_mul_i32 s100, s100, 0x80
	s_mul_i32 s99, s99, 0x40000
	s_add_u32 s100, s100, s99
	v_lshl_add_u64 v[118:119], s[100:101], 0, v[110:111]
	global_load_dwordx4 v[128:131], v[118:119], off
	s_waitcnt lgkmcnt(0)
	v_cvt_pk_bf16_f32 v120, v120, v121
	v_cvt_pk_bf16_f32 v121, v122, v123
	global_store_dwordx2 v[116:117], v[120:121], off
	s_add_u32 s98, s98, 0x100
	s_cmp_lt_u32 s98, 0x100
	s_cbranch_scc0 .Lcv_done_P0_watto
	s_waitcnt vmcnt(5)
	ds_write2_b32 v107, v136, v137 offset1:1
	ds_write2_b32 v107, v138, v139 offset0:2 offset1:3
	s_mov_b32 s99, s98
	s_lshr_b32 s100, s99, 3
	s_and_b32 s99, s99, 7
	s_mul_i32 s100, s100, 0x8000
	s_mul_i32 s99, s99, 0x80
	s_add_u32 s100, s100, s99
	v_lshl_add_u64 v[116:117], s[100:101], 0, v[114:115]
	s_waitcnt lgkmcnt(0)
	s_barrier
	ds_read2_b32 v[120:121], v134 offset1:33
	ds_read2_b32 v[122:123], v134 offset0:66 offset1:99
	s_add_u32 s99, s98, 0x300
	s_min_u32 s99, s99, 0xff
	s_lshr_b32 s100, s99, 3
	s_and_b32 s99, s99, 7
	s_mul_i32 s100, s100, 0x80
	s_mul_i32 s99, s99, 0x40000
	s_add_u32 s100, s100, s99
	v_lshl_add_u64 v[118:119], s[100:101], 0, v[110:111]
	global_load_dwordx4 v[136:139], v[118:119], off
	s_waitcnt lgkmcnt(0)
	v_cvt_pk_bf16_f32 v120, v120, v121
	v_cvt_pk_bf16_f32 v121, v122, v123
	global_store_dwordx2 v[116:117], v[120:121], off
	s_add_u32 s98, s98, 0x100
	s_cmp_lt_u32 s98, 0x100
	s_cbranch_scc0 .Lcv_done_P0_watto
	s_branch .Lcv_loop_P0_watto

.Lcv_none_P0_watto:
	s_cmp_lt_u32 s82, 0x200
	s_cbranch_scc0 .Lcv_none_P0_wrwo
	v_readlane_b32 s98, v254, 0
	v_readlane_b32 s99, v254, 1
	s_load_dwordx2 s[100:101], s[98:99], 0x98
	s_load_dwordx2 s[98:99], s[98:99], 0xe0
	v_mul_u32_u24_e32 v108, 0x1000, v101
	v_lshl_add_u32 v108, v102, 2, v108
	v_mul_u32_u24_e32 v112, 0x800, v103
	v_lshl_add_u32 v112, v104, 1, v112
	s_waitcnt lgkmcnt(0)
	v_lshl_add_u64 v[110:111], s[100:101], 0, v[108:109]
	s_add_u32 s98, s98, 0x100000
	s_addc_u32 s99, s99, 0
	v_lshl_add_u64 v[114:115], s[98:99], 0, v[112:113]
	s_mov_b32 s101, 0
	s_mov_b32 s98, s82
	s_mov_b32 s99, s98
	s_lshr_b32 s100, s99, 4
	s_and_b32 s99, s99, 15
	s_mul_i32 s100, s100, 0x80
	s_mul_i32 s99, s99, 0x40000
	s_add_u32 s100, s100, s99
	v_lshl_add_u64 v[118:119], s[100:101], 0, v[110:111]
	global_load_dwordx4 v[124:127], v[118:119], off
	s_add_u32 s99, s98, 0x100
	s_min_u32 s99, s99, 0x1ff
	s_lshr_b32 s100, s99, 4
	s_and_b32 s99, s99, 15
	s_mul_i32 s100, s100, 0x80
	s_mul_i32 s99, s99, 0x40000
	s_add_u32 s100, s100, s99
	v_lshl_add_u64 v[118:119], s[100:101], 0, v[110:111]
	global_load_dwordx4 v[128:131], v[118:119], off
	s_add_u32 s99, s98, 0x200
	s_min_u32 s99, s99, 0x1ff
	s_lshr_b32 s100, s99, 4
	s_and_b32 s99, s99, 15
	s_mul_i32 s100, s100, 0x80
	s_mul_i32 s99, s99, 0x40000
	s_add_u32 s100, s100, s99
	v_lshl_add_u64 v[118:119], s[100:101], 0, v[110:111]
	global_load_dwordx4 v[136:139], v[118:119], off
	s_waitcnt vmcnt(2)
	ds_write2_b32 v105, v124, v125 offset1:1
	ds_write2_b32 v105, v126, v127 offset0:2 offset1:3
	s_mov_b32 s99, s98
	s_lshr_b32 s100, s99, 4
	s_and_b32 s99, s99, 15
	s_mul_i32 s100, s100, 0x10000
	s_mul_i32 s99, s99, 0x80
	s_add_u32 s100, s100, s99
	v_lshl_add_u64 v[116:117], s[100:101], 0, v[114:115]
	s_waitcnt lgkmcnt(0)
	s_barrier
	ds_read2_b32 v[120:121], v132 offset1:33
	ds_read2_b32 v[122:123], v132 offset0:66 offset1:99
	s_add_u32 s99, s98, 0x300
	s_min_u32 s99, s99, 0x1ff
	s_lshr_b32 s100, s99, 4
	s_and_b32 s99, s99, 15
	s_mul_i32 s100, s100, 0x80
	s_mul_i32 s99, s99, 0x40000
	s_add_u32 s100, s100, s99
	v_lshl_add_u64 v[118:119], s[100:101], 0, v[110:111]
	global_load_dwordx4 v[124:127], v[118:119], off
	s_waitcnt lgkmcnt(0)
	v_cvt_pk_bf16_f32 v120, v120, v121
	v_cvt_pk_bf16_f32 v121, v122, v123
	global_store_dwordx2 v[116:117], v[120:121], off
	s_add_u32 s98, s98, 0x100
	s_cmp_lt_u32 s98, 0x200
	s_cbranch_scc0 .Lcv_done_P0_wrwo
	s_waitcnt vmcnt(3)
	ds_write2_b32 v106, v128, v129 offset1:1
	ds_write2_b32 v106, v130, v131 offset0:2 offset1:3
	s_mov_b32 s99, s98
	s_lshr_b32 s100, s99, 4
	s_and_b32 s99, s99, 15
	s_mul_i32 s100, s100, 0x10000
	s_mul_i32 s99, s99, 0x80
	s_add_u32 s100, s100, s99
	v_lshl_add_u64 v[116:117], s[100:101], 0, v[114:115]
	s_waitcnt lgkmcnt(0)
	s_barrier
	ds_read2_b32 v[120:121], v133 offset1:33
	ds_read2_b32 v[122:123], v133 offset0:66 offset1:99
	s_add_u32 s99, s98, 0x300
	s_min_u32 s99, s99, 0x1ff
	s_lshr_b32 s100, s99, 4
	s_and_b32 s99, s99, 15
	s_mul_i32 s100, s100, 0x80
	s_mul_i32 s99, s99, 0x40000
	s_add_u32 s100, s100, s99
	v_lshl_add_u64 v[118:119], s[100:101], 0, v[110:111]
	global_load_dwordx4 v[128:131], v[118:119], off
	s_waitcnt lgkmcnt(0)
	v_cvt_pk_bf16_f32 v120, v120, v121
	v_cvt_pk_bf16_f32 v121, v122, v123
	global_store_dwordx2 v[116:117], v[120:121], off
	s_add_u32 s98, s98, 0x100
	s_cmp_lt_u32 s98, 0x200
	s_cbranch_scc0 .Lcv_done_P0_wrwo
	s_waitcnt vmcnt(4)
	ds_write2_b32 v107, v136, v137 offset1:1
	ds_write2_b32 v107, v138, v139 offset0:2 offset1:3
	s_mov_b32 s99, s98
	s_lshr_b32 s100, s99, 4
	s_and_b32 s99, s99, 15
	s_mul_i32 s100, s100, 0x10000
	s_mul_i32 s99, s99, 0x80
	s_add_u32 s100, s100, s99
	v_lshl_add_u64 v[116:117], s[100:101], 0, v[114:115]
	s_waitcnt lgkmcnt(0)
	s_barrier
	ds_read2_b32 v[120:121], v134 offset1:33
	ds_read2_b32 v[122:123], v134 offset0:66 offset1:99
	s_add_u32 s99, s98, 0x300
	s_min_u32 s99, s99, 0x1ff
	s_lshr_b32 s100, s99, 4
	s_and_b32 s99, s99, 15
	s_mul_i32 s100, s100, 0x80
	s_mul_i32 s99, s99, 0x40000
	s_add_u32 s100, s100, s99
	v_lshl_add_u64 v[118:119], s[100:101], 0, v[110:111]
	global_load_dwordx4 v[136:139], v[118:119], off
	s_waitcnt lgkmcnt(0)
	v_cvt_pk_bf16_f32 v120, v120, v121
	v_cvt_pk_bf16_f32 v121, v122, v123
	global_store_dwordx2 v[116:117], v[120:121], off
	s_add_u32 s98, s98, 0x100
	s_cmp_lt_u32 s98, 0x200
	s_cbranch_scc0 .Lcv_done_P0_wrwo
.Lcv_loop_P0_wrwo:
	s_waitcnt vmcnt(5)
	ds_write2_b32 v105, v124, v125 offset1:1
	ds_write2_b32 v105, v126, v127 offset0:2 offset1:3
	s_mov_b32 s99, s98
	s_lshr_b32 s100, s99, 4
	s_and_b32 s99, s99, 15
	s_mul_i32 s100, s100, 0x10000
	s_mul_i32 s99, s99, 0x80
	s_add_u32 s100, s100, s99
	v_lshl_add_u64 v[116:117], s[100:101], 0, v[114:115]
	s_waitcnt lgkmcnt(0)
	s_barrier
	ds_read2_b32 v[120:121], v132 offset1:33
	ds_read2_b32 v[122:123], v132 offset0:66 offset1:99
	s_add_u32 s99, s98, 0x300
	s_min_u32 s99, s99, 0x1ff
	s_lshr_b32 s100, s99, 4
	s_and_b32 s99, s99, 15
	s_mul_i32 s100, s100, 0x80
	s_mul_i32 s99, s99, 0x40000
	s_add_u32 s100, s100, s99
	v_lshl_add_u64 v[118:119], s[100:101], 0, v[110:111]
	global_load_dwordx4 v[124:127], v[118:119], off
	s_waitcnt lgkmcnt(0)
	v_cvt_pk_bf16_f32 v120, v120, v121
	v_cvt_pk_bf16_f32 v121, v122, v123
	global_store_dwordx2 v[116:117], v[120:121], off
	s_add_u32 s98, s98, 0x100
	s_cmp_lt_u32 s98, 0x200
	s_cbranch_scc0 .Lcv_done_P0_wrwo
	s_waitcnt vmcnt(5)
	ds_write2_b32 v106, v128, v129 offset1:1
	ds_write2_b32 v106, v130, v131 offset0:2 offset1:3
	s_mov_b32 s99, s98
	s_lshr_b32 s100, s99, 4
	s_and_b32 s99, s99, 15
	s_mul_i32 s100, s100, 0x10000
	s_mul_i32 s99, s99, 0x80
	s_add_u32 s100, s100, s99
	v_lshl_add_u64 v[116:117], s[100:101], 0, v[114:115]
	s_waitcnt lgkmcnt(0)
	s_barrier
	ds_read2_b32 v[120:121], v133 offset1:33
	ds_read2_b32 v[122:123], v133 offset0:66 offset1:99
	s_add_u32 s99, s98, 0x300
	s_min_u32 s99, s99, 0x1ff
	s_lshr_b32 s100, s99, 4
	s_and_b32 s99, s99, 15
	s_mul_i32 s100, s100, 0x80
	s_mul_i32 s99, s99, 0x40000
	s_add_u32 s100, s100, s99
	v_lshl_add_u64 v[118:119], s[100:101], 0, v[110:111]
	global_load_dwordx4 v[128:131], v[118:119], off
	s_waitcnt lgkmcnt(0)
	v_cvt_pk_bf16_f32 v120, v120, v121
	v_cvt_pk_bf16_f32 v121, v122, v123
	global_store_dwordx2 v[116:117], v[120:121], off
	s_add_u32 s98, s98, 0x100
	s_cmp_lt_u32 s98, 0x200
	s_cbranch_scc0 .Lcv_done_P0_wrwo
	s_waitcnt vmcnt(5)
	ds_write2_b32 v107, v136, v137 offset1:1
	ds_write2_b32 v107, v138, v139 offset0:2 offset1:3
	s_mov_b32 s99, s98
	s_lshr_b32 s100, s99, 4
	s_and_b32 s99, s99, 15
	s_mul_i32 s100, s100, 0x10000
	s_mul_i32 s99, s99, 0x80
	s_add_u32 s100, s100, s99
	v_lshl_add_u64 v[116:117], s[100:101], 0, v[114:115]
	s_waitcnt lgkmcnt(0)
	s_barrier
	ds_read2_b32 v[120:121], v134 offset1:33
	ds_read2_b32 v[122:123], v134 offset0:66 offset1:99
	s_add_u32 s99, s98, 0x300
	s_min_u32 s99, s99, 0x1ff
	s_lshr_b32 s100, s99, 4
	s_and_b32 s99, s99, 15
	s_mul_i32 s100, s100, 0x80
	s_mul_i32 s99, s99, 0x40000
	s_add_u32 s100, s100, s99
	v_lshl_add_u64 v[118:119], s[100:101], 0, v[110:111]
	global_load_dwordx4 v[136:139], v[118:119], off
	s_waitcnt lgkmcnt(0)
	v_cvt_pk_bf16_f32 v120, v120, v121
	v_cvt_pk_bf16_f32 v121, v122, v123
	global_store_dwordx2 v[116:117], v[120:121], off
	s_add_u32 s98, s98, 0x100
	s_cmp_lt_u32 s98, 0x200
	s_cbranch_scc0 .Lcv_done_P0_wrwo
	s_branch .Lcv_loop_P0_wrwo

.Lcv_none_P0_wrwo:
	s_cmp_lt_u32 s82, 0x200
	s_cbranch_scc0 .Lcv_none_P0_wo
	v_readlane_b32 s98, v254, 0
	v_readlane_b32 s99, v254, 1
	s_load_dwordx2 s[100:101], s[98:99], 0xa0
	s_load_dwordx2 s[98:99], s[98:99], 0xe0
	v_mul_u32_u24_e32 v108, 0x1000, v101
	v_lshl_add_u32 v108, v102, 2, v108
	v_mul_u32_u24_e32 v112, 0x800, v103
	v_lshl_add_u32 v112, v104, 1, v112
	s_waitcnt lgkmcnt(0)
	v_lshl_add_u64 v[110:111], s[100:101], 0, v[108:109]
	s_add_u32 s98, s98, 0x300000
	s_addc_u32 s99, s99, 0
	v_lshl_add_u64 v[114:115], s[98:99], 0, v[112:113]
	s_mov_b32 s101, 0
	s_mov_b32 s98, s82
	s_mov_b32 s99, s98
	s_lshr_b32 s100, s99, 4
	s_and_b32 s99, s99, 15
	s_mul_i32 s100, s100, 0x80
	s_mul_i32 s99, s99, 0x40000
	s_add_u32 s100, s100, s99
	v_lshl_add_u64 v[118:119], s[100:101], 0, v[110:111]
	global_load_dwordx4 v[124:127], v[118:119], off
	s_add_u32 s99, s98, 0x100
	s_min_u32 s99, s99, 0x1ff
	s_lshr_b32 s100, s99, 4
	s_and_b32 s99, s99, 15
	s_mul_i32 s100, s100, 0x80
	s_mul_i32 s99, s99, 0x40000
	s_add_u32 s100, s100, s99
	v_lshl_add_u64 v[118:119], s[100:101], 0, v[110:111]
	global_load_dwordx4 v[128:131], v[118:119], off
	s_add_u32 s99, s98, 0x200
	s_min_u32 s99, s99, 0x1ff
	s_lshr_b32 s100, s99, 4
	s_and_b32 s99, s99, 15
	s_mul_i32 s100, s100, 0x80
	s_mul_i32 s99, s99, 0x40000
	s_add_u32 s100, s100, s99
	v_lshl_add_u64 v[118:119], s[100:101], 0, v[110:111]
	global_load_dwordx4 v[136:139], v[118:119], off
	s_waitcnt vmcnt(2)
	ds_write2_b32 v105, v124, v125 offset1:1
	ds_write2_b32 v105, v126, v127 offset0:2 offset1:3
	s_mov_b32 s99, s98
	s_lshr_b32 s100, s99, 4
	s_and_b32 s99, s99, 15
	s_mul_i32 s100, s100, 0x10000
	s_mul_i32 s99, s99, 0x80
	s_add_u32 s100, s100, s99
	v_lshl_add_u64 v[116:117], s[100:101], 0, v[114:115]
	s_waitcnt lgkmcnt(0)
	s_barrier
	ds_read2_b32 v[120:121], v132 offset1:33
	ds_read2_b32 v[122:123], v132 offset0:66 offset1:99
	s_add_u32 s99, s98, 0x300
	s_min_u32 s99, s99, 0x1ff
	s_lshr_b32 s100, s99, 4
	s_and_b32 s99, s99, 15
	s_mul_i32 s100, s100, 0x80
	s_mul_i32 s99, s99, 0x40000
	s_add_u32 s100, s100, s99
	v_lshl_add_u64 v[118:119], s[100:101], 0, v[110:111]
	global_load_dwordx4 v[124:127], v[118:119], off
	s_waitcnt lgkmcnt(0)
	v_cvt_pk_bf16_f32 v120, v120, v121
	v_cvt_pk_bf16_f32 v121, v122, v123
	global_store_dwordx2 v[116:117], v[120:121], off
	s_add_u32 s98, s98, 0x100
	s_cmp_lt_u32 s98, 0x200
	s_cbranch_scc0 .Lcv_done_P0_wo
	s_waitcnt vmcnt(3)
	ds_write2_b32 v106, v128, v129 offset1:1
	ds_write2_b32 v106, v130, v131 offset0:2 offset1:3
	s_mov_b32 s99, s98
	s_lshr_b32 s100, s99, 4
	s_and_b32 s99, s99, 15
	s_mul_i32 s100, s100, 0x10000
	s_mul_i32 s99, s99, 0x80
	s_add_u32 s100, s100, s99
	v_lshl_add_u64 v[116:117], s[100:101], 0, v[114:115]
	s_waitcnt lgkmcnt(0)
	s_barrier
	ds_read2_b32 v[120:121], v133 offset1:33
	ds_read2_b32 v[122:123], v133 offset0:66 offset1:99
	s_add_u32 s99, s98, 0x300
	s_min_u32 s99, s99, 0x1ff
	s_lshr_b32 s100, s99, 4
	s_and_b32 s99, s99, 15
	s_mul_i32 s100, s100, 0x80
	s_mul_i32 s99, s99, 0x40000
	s_add_u32 s100, s100, s99
	v_lshl_add_u64 v[118:119], s[100:101], 0, v[110:111]
	global_load_dwordx4 v[128:131], v[118:119], off
	s_waitcnt lgkmcnt(0)
	v_cvt_pk_bf16_f32 v120, v120, v121
	v_cvt_pk_bf16_f32 v121, v122, v123
	global_store_dwordx2 v[116:117], v[120:121], off
	s_add_u32 s98, s98, 0x100
	s_cmp_lt_u32 s98, 0x200
	s_cbranch_scc0 .Lcv_done_P0_wo
	s_waitcnt vmcnt(4)
	ds_write2_b32 v107, v136, v137 offset1:1
	ds_write2_b32 v107, v138, v139 offset0:2 offset1:3
	s_mov_b32 s99, s98
	s_lshr_b32 s100, s99, 4
	s_and_b32 s99, s99, 15
	s_mul_i32 s100, s100, 0x10000
	s_mul_i32 s99, s99, 0x80
	s_add_u32 s100, s100, s99
	v_lshl_add_u64 v[116:117], s[100:101], 0, v[114:115]
	s_waitcnt lgkmcnt(0)
	s_barrier
	ds_read2_b32 v[120:121], v134 offset1:33
	ds_read2_b32 v[122:123], v134 offset0:66 offset1:99
	s_add_u32 s99, s98, 0x300
	s_min_u32 s99, s99, 0x1ff
	s_lshr_b32 s100, s99, 4
	s_and_b32 s99, s99, 15
	s_mul_i32 s100, s100, 0x80
	s_mul_i32 s99, s99, 0x40000
	s_add_u32 s100, s100, s99
	v_lshl_add_u64 v[118:119], s[100:101], 0, v[110:111]
	global_load_dwordx4 v[136:139], v[118:119], off
	s_waitcnt lgkmcnt(0)
	v_cvt_pk_bf16_f32 v120, v120, v121
	v_cvt_pk_bf16_f32 v121, v122, v123
	global_store_dwordx2 v[116:117], v[120:121], off
	s_add_u32 s98, s98, 0x100
	s_cmp_lt_u32 s98, 0x200
	s_cbranch_scc0 .Lcv_done_P0_wo

.Lcv_skip_P0:
	s_ashr_i32 s16, s82, 31
	v_readlane_b32 s4, v254, 0
	v_readlane_b32 s8, v254, 2
	s_lshr_b32 s0, s16, 28
	v_readlane_b32 s5, v254, 1
	s_mov_b32 s14, s8
	s_add_i32 s0, s82, s0
	s_load_dwordx2 s[6:7], s[4:5], 0xe0
	v_mbcnt_lo_u32_b32 v14, -1, 0
	v_mbcnt_hi_u32_b32 v14, -1, v14
	s_load_dwordx2 s[2:3], s[4:5], 0x28
	s_and_b32 s1, s0, 0x3fffff0
	s_lshl_b32 s0, s0, 1
	s_sub_i32 s1, s82, s1
	s_andn2_b32 s0, s0, 31
	s_lshl_b32 s15, s1, 6
	s_ashr_i32 s1, s0, 31
	s_cmpk_gt_i32 s82, 0x68f
	v_mbcnt_lo_u32_b32 v0, -1, 0
	v_mbcnt_hi_u32_b32 v0, -1, v0
	s_cbranch_scc1 .LBB0_23
	s_cmpk_eq_i32 s80, 0x100
	s_cbranch_scc1 .LBB0_23
	v_lshl_add_u32 v5, s8, 6, v0
	v_ashrrev_i32_e32 v7, 3, v5
	v_lshlrev_b32_e32 v6, 2, v5
	v_add_u32_e32 v2, s15, v7
	s_mov_b32 s17, 0x9c80
	s_waitcnt lgkmcnt(0)
	v_mov_b64_e32 v[0:1], s[2:3]
	v_and_b32_e32 v4, 28, v6
	v_mad_i64_i32 v[0:1], s[8:9], v2, s17, v[0:1]
	v_lshl_add_u64 v[0:1], s[0:1], 2, v[0:1]
	v_mov_b32_e32 v9, 0
	v_lshlrev_b32_e32 v8, 2, v4
	v_lshl_add_u64 v[0:1], v[0:1], 0, v[8:9]
	s_movk_i32 s8, 0x4000
	v_add_co_u32_e32 v0, vcc, s8, v0
	s_add_u32 s8, s6, 0x800000
	s_nop 0
	v_addc_co_u32_e32 v1, vcc, 0, v1, vcc
	global_load_dwordx4 v[0:3], v[0:1], off offset:2048
	s_addc_u32 s9, s7, 0
	v_and_b32_e32 v6, 60, v6
	v_ashrrev_i32_e32 v12, 4, v5
	s_add_u32 s10, s2, 0x4800
	s_movk_i32 s12, 0x84
	v_add_u32_e32 v5, 0, v8
	s_addc_u32 s11, s3, 0
	v_mul_lo_u32 v10, v7, s12
	v_mul_u32_u24_e32 v8, 0x84, v6
	v_lshlrev_b32_e32 v11, 2, v12
	s_lshl_b32 s19, s80, 6
	v_add3_u32 v13, 0, v8, v11
	v_add_u32_e32 v15, s19, v7
	v_lshlrev_b32_e32 v8, 2, v4
	v_add_u32_e32 v16, v5, v10
	v_lshlrev_b32_e32 v10, 1, v6
	s_lshl_b32 s18, s82, 6
	v_mov_b32_e32 v11, v9
	s_mov_b32 s21, s82
	s_waitcnt vmcnt(0)
	v_mov_b64_e32 v[6:7], v[2:3]
	v_mov_b64_e32 v[4:5], v[0:1]
	s_branch .LBB0_21

.LBB0_23:
	s_waitcnt lgkmcnt(0)
	s_add_u32 s8, s6, 0xf00000
	s_addc_u32 s9, s7, 0
	s_cmpk_gt_i32 s82, 0x8ff
	v_readlane_b32 s10, v254, 2
	v_mbcnt_lo_u32_b32 v0, -1, 0
	v_mbcnt_hi_u32_b32 v0, -1, v0
	s_cbranch_scc1 .LBB0_28
	s_cmpk_eq_i32 s80, 0x100
	s_cbranch_scc1 .LBB0_28
	s_nop 0
	v_lshl_add_u32 v1, s10, 6, v0
	v_ashrrev_i32_e32 v12, 3, v1
	v_lshlrev_b32_e32 v13, 2, v1
	v_add_u32_e32 v2, s15, v12
	s_mov_b32 s12, 0x9c80
	v_mov_b64_e32 v[8:9], s[2:3]
	v_and_b32_e32 v0, 28, v13
	v_mad_i64_i32 v[2:3], s[10:11], v2, s12, v[8:9]
	v_lshl_add_u64 v[2:3], s[0:1], 2, v[2:3]
	v_mov_b32_e32 v11, 0
	v_lshlrev_b32_e32 v10, 2, v0
	v_lshl_add_u64 v[2:3], v[2:3], 0, v[10:11]
	global_load_dwordx4 v[4:7], v[2:3], off
	v_and_b32_e32 v2, 60, v13
	v_ashrrev_i32_e32 v15, 4, v1
	s_movk_i32 s10, 0x84
	v_add_u32_e32 v1, 0, v10
	v_mul_lo_u32 v3, v12, s10
	v_mul_u32_u24_e32 v10, 0x84, v2
	v_lshlrev_b32_e32 v13, 2, v15
	s_lshl_b32 s17, s80, 6
	v_add3_u32 v16, 0, v10, v13
	v_add_u32_e32 v17, s17, v12
	v_lshlrev_b32_e32 v10, 2, v0
	v_add_u32_e32 v18, v1, v3
	v_lshlrev_b32_e32 v12, 1, v2
	s_lshl_b32 s13, s82, 6
	v_mov_b32_e32 v13, v11
	s_mov_b32 s19, s82
	s_waitcnt vmcnt(0)
	v_mov_b64_e32 v[0:1], v[4:5]
	v_mov_b64_e32 v[2:3], v[6:7]
	s_branch .LBB0_26

.LBB0_28:
	s_cmpk_gt_i32 s82, 0x3ff
	v_readlane_b32 s10, v254, 2
	v_mbcnt_lo_u32_b32 v0, -1, 0
	v_mbcnt_hi_u32_b32 v0, -1, v0
	s_cbranch_scc1 .LBB0_33
	s_cmpk_eq_i32 s80, 0x100
	s_cbranch_scc1 .LBB0_33
	s_nop 0
	v_lshl_add_u32 v5, s10, 6, v0
	v_ashrrev_i32_e32 v7, 3, v5
	v_lshlrev_b32_e32 v6, 2, v5
	v_add_u32_e32 v2, s15, v7
	s_mov_b32 s12, 0x9c80
	v_mov_b64_e32 v[0:1], s[2:3]
	v_and_b32_e32 v4, 28, v6
	v_mad_i64_i32 v[0:1], s[10:11], v2, s12, v[0:1]
	v_lshl_add_u64 v[0:1], s[0:1], 2, v[0:1]
	v_mov_b32_e32 v9, 0
	v_lshlrev_b32_e32 v8, 2, v4
	v_lshl_add_u64 v[0:1], v[0:1], 0, v[8:9]
	s_movk_i32 s10, 0x7000
	v_add_co_u32_e32 v0, vcc, s10, v0
	v_and_b32_e32 v6, 60, v6
	s_nop 0
	v_addc_co_u32_e32 v1, vcc, 0, v1, vcc
	global_load_dwordx4 v[0:3], v[0:1], off offset:3200
	v_ashrrev_i32_e32 v5, 4, v5
	s_add_u32 s2, s2, 0x7c80
	s_movk_i32 s10, 0x84
	v_add_u32_e32 v10, 0, v8
	s_addc_u32 s3, s3, 0
	v_mul_lo_u32 v11, v7, s10
	v_mul_u32_u24_e32 v8, 0x84, v6
	v_lshlrev_b32_e32 v12, 2, v5
	s_lshl_b32 s17, s80, 6
	v_add3_u32 v12, 0, v8, v12
	v_add_u32_e32 v13, 0x1200, v5
	v_add_u32_e32 v15, s17, v7
	v_lshlrev_b32_e32 v8, 2, v4
	v_add_u32_e32 v16, v10, v11
	v_lshlrev_b32_e32 v10, 1, v6
	s_lshl_b32 s13, s82, 6
	v_mov_b32_e32 v11, v9
	s_mov_b32 s19, s82
	s_waitcnt vmcnt(0)
	v_mov_b64_e32 v[6:7], v[2:3]
	v_mov_b64_e32 v[4:5], v[0:1]
	s_branch .LBB0_31

.LBB0_33:
	s_cmpk_gt_i32 s82, 0xff
	v_readlane_b32 s8, v254, 2
	v_mbcnt_lo_u32_b32 v0, -1, 0
	v_mbcnt_hi_u32_b32 v0, -1, v0
	s_cbranch_scc1 .LBB0_38
	s_cmpk_eq_i32 s80, 0x100
	s_cbranch_scc1 .LBB0_38
	s_nop 0
	v_lshl_add_u32 v1, s8, 6, v0
	s_lshr_b32 s8, s16, 29
	s_add_i32 s8, s82, s8
	s_load_dwordx2 s[2:3], s[4:5], 0x90
	s_and_b32 s9, s8, 0x3fffff8
	v_ashrrev_i32_e32 v10, 3, v1
	s_sub_i32 s10, s82, s9
	v_lshl_add_u32 v2, s10, 6, v10
	s_lshl_b32 s8, s8, 2
	v_ashrrev_i32_e32 v3, 31, v2
	s_andn2_b32 s8, s8, 31
	v_lshlrev_b32_e32 v11, 2, v1
	v_lshlrev_b64 v[2:3], 12, v[2:3]
	s_ashr_i32 s9, s8, 31
	v_and_b32_e32 v0, 28, v11
	s_waitcnt lgkmcnt(0)
	v_lshl_add_u64 v[2:3], s[2:3], 0, v[2:3]
	v_lshl_add_u64 v[2:3], s[8:9], 2, v[2:3]
	v_mov_b32_e32 v9, 0
	v_lshlrev_b32_e32 v8, 2, v0
	v_lshl_add_u64 v[2:3], v[2:3], 0, v[8:9]
	global_load_dwordx4 v[4:7], v[2:3], off
	v_and_b32_e32 v2, 60, v11
	v_ashrrev_i32_e32 v12, 4, v1
	s_movk_i32 s8, 0x84
	v_add_u32_e32 v1, 0, v8
	v_mul_lo_u32 v3, v10, s8
	v_mul_u32_u24_e32 v8, 0x84, v2
	v_lshlrev_b32_e32 v11, 2, v12
	s_lshl_b32 s11, s80, 6
	v_add3_u32 v13, 0, v8, v11
	v_add_u32_e32 v15, s11, v10
	v_lshlrev_b32_e32 v8, 2, v0
	v_add_u32_e32 v16, v1, v3
	v_lshlrev_b32_e32 v10, 1, v2
	s_lshl_b32 s10, s82, 6
	v_mov_b32_e32 v11, v9
	s_mov_b32 s13, s82
	s_waitcnt vmcnt(0)
	v_mov_b64_e32 v[0:1], v[4:5]
	v_mov_b64_e32 v[2:3], v[6:7]
	s_branch .LBB0_36

.LBB0_38:
	s_cmpk_lt_i32 s82, 0x200
	s_cselect_b64 s[2:3], -1, 0
	s_cmpk_gt_i32 s82, 0x1ff
	v_readlane_b32 s10, v254, 2
	v_mbcnt_lo_u32_b32 v0, -1, 0
	v_mbcnt_hi_u32_b32 v0, -1, v0
	s_cbranch_scc1 .LBB0_43
	s_cmpk_eq_i32 s80, 0x100
	s_cbranch_scc1 .LBB0_43
	s_load_dwordx2 s[8:9], s[4:5], 0x98
	v_lshl_add_u32 v5, s10, 6, v0
	v_ashrrev_i32_e32 v7, 3, v5
	v_add_u32_e32 v0, s15, v7
	v_ashrrev_i32_e32 v1, 31, v0
	v_lshlrev_b32_e32 v6, 2, v5
	v_lshlrev_b64 v[0:1], 12, v[0:1]
	v_and_b32_e32 v4, 28, v6
	s_waitcnt lgkmcnt(0)
	v_lshl_add_u64 v[0:1], s[8:9], 0, v[0:1]
	v_lshl_add_u64 v[0:1], s[0:1], 2, v[0:1]
	v_mov_b32_e32 v9, 0
	v_lshlrev_b32_e32 v8, 2, v4
	v_lshl_add_u64 v[0:1], v[0:1], 0, v[8:9]
	global_load_dwordx4 v[0:3], v[0:1], off
	s_add_u32 s10, s6, 0x100000
	v_and_b32_e32 v6, 60, v6
	v_ashrrev_i32_e32 v12, 4, v5
	s_movk_i32 s12, 0x84
	s_addc_u32 s11, s7, 0
	v_add_u32_e32 v5, 0, v8
	v_mul_lo_u32 v10, v7, s12
	v_mul_u32_u24_e32 v8, 0x84, v6
	v_lshlrev_b32_e32 v11, 2, v12
	s_lshl_b32 s17, s80, 6
	v_add3_u32 v13, 0, v8, v11
	v_add_u32_e32 v15, s17, v7
	v_lshlrev_b32_e32 v8, 2, v4
	v_add_u32_e32 v16, v5, v10
	v_lshlrev_b32_e32 v10, 1, v6
	s_lshl_b32 s16, s82, 6
	v_mov_b32_e32 v11, v9
	s_mov_b32 s19, s82
	s_waitcnt vmcnt(0)
	v_mov_b64_e32 v[6:7], v[2:3]
	v_mov_b64_e32 v[4:5], v[0:1]
	s_branch .LBB0_41

.LBB0_43:
	v_readlane_b32 s8, v254, 2
	s_andn2_b64 vcc, exec, s[2:3]
	v_mbcnt_lo_u32_b32 v0, -1, 0
	v_mbcnt_hi_u32_b32 v0, -1, v0
	s_cbranch_vccnz .LBB0_48
	s_cmpk_eq_i32 s80, 0x100
	s_cbranch_scc1 .LBB0_48
	s_load_dwordx2 s[2:3], s[4:5], 0xa0
	v_lshl_add_u32 v5, s8, 6, v0
	v_ashrrev_i32_e32 v7, 3, v5
	v_add_u32_e32 v0, s15, v7
	v_ashrrev_i32_e32 v1, 31, v0
	v_lshlrev_b32_e32 v6, 2, v5
	v_lshlrev_b64 v[0:1], 12, v[0:1]
	v_and_b32_e32 v4, 28, v6
	s_waitcnt lgkmcnt(0)
	v_lshl_add_u64 v[0:1], s[2:3], 0, v[0:1]
	v_lshl_add_u64 v[0:1], s[0:1], 2, v[0:1]
	v_mov_b32_e32 v9, 0
	v_lshlrev_b32_e32 v8, 2, v4
	v_lshl_add_u64 v[0:1], v[0:1], 0, v[8:9]
	global_load_dwordx4 v[0:3], v[0:1], off
	s_add_u32 s0, s6, 0x300000
	v_and_b32_e32 v6, 60, v6
	v_ashrrev_i32_e32 v12, 4, v5
	s_movk_i32 s8, 0x84
	s_addc_u32 s1, s7, 0
	v_add_u32_e32 v5, 0, v8
	v_mul_lo_u32 v10, v7, s8
	v_mul_u32_u24_e32 v8, 0x84, v6
	v_lshlrev_b32_e32 v11, 2, v12
	s_lshl_b32 s11, s80, 6
	v_add3_u32 v13, 0, v8, v11
	v_add_u32_e32 v15, s11, v7
	v_lshlrev_b32_e32 v8, 2, v4
	v_add_u32_e32 v16, v5, v10
	v_lshlrev_b32_e32 v10, 1, v6
	s_lshl_b32 s10, s82, 6
	v_mov_b32_e32 v11, v9
	s_mov_b32 s13, s82
	s_waitcnt vmcnt(0)
	v_mov_b64_e32 v[6:7], v[2:3]
	v_mov_b64_e32 v[4:5], v[0:1]
	s_branch .LBB0_46

.LBB0_1251:
.LBB0_1252:
	s_waitcnt lgkmcnt(0)
	v_readlane_b32 s98, v254, 5
	s_nop 0
	s_cmpk_lg_i32 s98, 0x100
	s_cbranch_scc1 .Lcv_skip_P15
	v_mbcnt_lo_u32_b32 v100, -1, 0
	v_mbcnt_hi_u32_b32 v100, -1, v100
	v_readlane_b32 s98, v254, 2
	s_nop 2
	v_lshl_add_u32 v100, s98, 6, v100
	v_lshrrev_b32_e32 v101, 3, v100
	v_and_b32_e32 v102, 7, v100
	v_lshlrev_b32_e32 v102, 2, v102
	v_lshrrev_b32_e32 v103, 4, v100
	v_and_b32_e32 v104, 15, v100
	v_lshlrev_b32_e32 v104, 2, v104
	v_mul_u32_u24_e32 v105, 33, v101
	v_add_u32_e32 v105, v105, v102
	v_lshlrev_b32_e32 v105, 2, v105
	v_add_u32_e32 v106, 0x2100, v105
	v_add_u32_e32 v107, 0x4200, v105
	v_mul_u32_u24_e32 v132, 33, v104
	v_add_u32_e32 v132, v132, v103
	v_lshlrev_b32_e32 v132, 2, v132
	v_add_u32_e32 v133, 0x2100, v132
	v_add_u32_e32 v134, 0x4200, v132
	v_mov_b32_e32 v109, 0
	v_mov_b32_e32 v113, 0
	s_cmp_lt_u32 s82, 0xb00
	s_cbranch_scc0 .Lcv_none_P15_wup
	v_readlane_b32 s98, v254, 0
	v_readlane_b32 s99, v254, 1
	s_load_dwordx2 s[100:101], s[98:99], 0xb0
	s_load_dwordx2 s[98:99], s[98:99], 0xe0
	v_mul_u32_u24_e32 v108, 0x5800, v101
	v_lshl_add_u32 v108, v102, 2, v108
	v_mul_u32_u24_e32 v112, 0x800, v103
	v_lshl_add_u32 v112, v104, 1, v112
	s_waitcnt lgkmcnt(0)
	v_lshl_add_u64 v[110:111], s[100:101], 0, v[108:109]
	s_add_u32 s98, s98, 0x800000
	s_addc_u32 s99, s99, 0
	v_lshl_add_u64 v[114:115], s[98:99], 0, v[112:113]
	s_mov_b32 s101, 0
	s_mov_b32 s98, s82
	s_mov_b32 s99, s98
	s_lshr_b32 s100, s99, 4
	s_and_b32 s99, s99, 15
	s_mul_i32 s100, s100, 0x80
	s_mul_i32 s99, s99, 0x160000
	s_add_u32 s100, s100, s99
	v_lshl_add_u64 v[118:119], s[100:101], 0, v[110:111]
	global_load_dwordx4 v[124:127], v[118:119], off
	s_add_u32 s99, s98, 0x100
	s_min_u32 s99, s99, 0xaff
	s_lshr_b32 s100, s99, 4
	s_and_b32 s99, s99, 15
	s_mul_i32 s100, s100, 0x80
	s_mul_i32 s99, s99, 0x160000
	s_add_u32 s100, s100, s99
	v_lshl_add_u64 v[118:119], s[100:101], 0, v[110:111]
	global_load_dwordx4 v[128:131], v[118:119], off
	s_add_u32 s99, s98, 0x200
	s_min_u32 s99, s99, 0xaff
	s_lshr_b32 s100, s99, 4
	s_and_b32 s99, s99, 15
	s_mul_i32 s100, s100, 0x80
	s_mul_i32 s99, s99, 0x160000
	s_add_u32 s100, s100, s99
	v_lshl_add_u64 v[118:119], s[100:101], 0, v[110:111]
	global_load_dwordx4 v[136:139], v[118:119], off
	s_waitcnt vmcnt(2)
	ds_write2_b32 v105, v124, v125 offset1:1
	ds_write2_b32 v105, v126, v127 offset0:2 offset1:3
	s_mov_b32 s99, s98
	s_lshr_b32 s100, s99, 4
	s_and_b32 s99, s99, 15
	s_mul_i32 s100, s100, 0x10000
	s_mul_i32 s99, s99, 0x80
	s_add_u32 s100, s100, s99
	v_lshl_add_u64 v[116:117], s[100:101], 0, v[114:115]
	s_waitcnt lgkmcnt(0)
	s_barrier
	ds_read2_b32 v[120:121], v132 offset1:33
	ds_read2_b32 v[122:123], v132 offset0:66 offset1:99
	s_add_u32 s99, s98, 0x300
	s_min_u32 s99, s99, 0xaff
	s_lshr_b32 s100, s99, 4
	s_and_b32 s99, s99, 15
	s_mul_i32 s100, s100, 0x80
	s_mul_i32 s99, s99, 0x160000
	s_add_u32 s100, s100, s99
	v_lshl_add_u64 v[118:119], s[100:101], 0, v[110:111]
	global_load_dwordx4 v[124:127], v[118:119], off
	s_waitcnt lgkmcnt(0)
	v_cvt_pk_bf16_f32 v120, v120, v121
	v_cvt_pk_bf16_f32 v121, v122, v123
	global_store_dwordx2 v[116:117], v[120:121], off
	s_add_u32 s98, s98, 0x100
	s_cmp_lt_u32 s98, 0xb00
	s_cbranch_scc0 .Lcv_done_P15_wup
	s_waitcnt vmcnt(3)
	ds_write2_b32 v106, v128, v129 offset1:1
	ds_write2_b32 v106, v130, v131 offset0:2 offset1:3
	s_mov_b32 s99, s98
	s_lshr_b32 s100, s99, 4
	s_and_b32 s99, s99, 15
	s_mul_i32 s100, s100, 0x10000
	s_mul_i32 s99, s99, 0x80
	s_add_u32 s100, s100, s99
	v_lshl_add_u64 v[116:117], s[100:101], 0, v[114:115]
	s_waitcnt lgkmcnt(0)
	s_barrier
	ds_read2_b32 v[120:121], v133 offset1:33
	ds_read2_b32 v[122:123], v133 offset0:66 offset1:99
	s_add_u32 s99, s98, 0x300
	s_min_u32 s99, s99, 0xaff
	s_lshr_b32 s100, s99, 4
	s_and_b32 s99, s99, 15
	s_mul_i32 s100, s100, 0x80
	s_mul_i32 s99, s99, 0x160000
	s_add_u32 s100, s100, s99
	v_lshl_add_u64 v[118:119], s[100:101], 0, v[110:111]
	global_load_dwordx4 v[128:131], v[118:119], off
	s_waitcnt lgkmcnt(0)
	v_cvt_pk_bf16_f32 v120, v120, v121
	v_cvt_pk_bf16_f32 v121, v122, v123
	global_store_dwordx2 v[116:117], v[120:121], off
	s_add_u32 s98, s98, 0x100
	s_cmp_lt_u32 s98, 0xb00
	s_cbranch_scc0 .Lcv_done_P15_wup
	s_waitcnt vmcnt(4)
	ds_write2_b32 v107, v136, v137 offset1:1
	ds_write2_b32 v107, v138, v139 offset0:2 offset1:3
	s_mov_b32 s99, s98
	s_lshr_b32 s100, s99, 4
	s_and_b32 s99, s99, 15
	s_mul_i32 s100, s100, 0x10000
	s_mul_i32 s99, s99, 0x80
	s_add_u32 s100, s100, s99
	v_lshl_add_u64 v[116:117], s[100:101], 0, v[114:115]
	s_waitcnt lgkmcnt(0)
	s_barrier
	ds_read2_b32 v[120:121], v134 offset1:33
	ds_read2_b32 v[122:123], v134 offset0:66 offset1:99
	s_add_u32 s99, s98, 0x300
	s_min_u32 s99, s99, 0xaff
	s_lshr_b32 s100, s99, 4
	s_and_b32 s99, s99, 15
	s_mul_i32 s100, s100, 0x80
	s_mul_i32 s99, s99, 0x160000
	s_add_u32 s100, s100, s99
	v_lshl_add_u64 v[118:119], s[100:101], 0, v[110:111]
	global_load_dwordx4 v[136:139], v[118:119], off
	s_waitcnt lgkmcnt(0)
	v_cvt_pk_bf16_f32 v120, v120, v121
	v_cvt_pk_bf16_f32 v121, v122, v123
	global_store_dwordx2 v[116:117], v[120:121], off
	s_add_u32 s98, s98, 0x100
	s_cmp_lt_u32 s98, 0xb00
	s_cbranch_scc0 .Lcv_done_P15_wup
.Lcv_loop_P15_wup:
	s_waitcnt vmcnt(5)
	ds_write2_b32 v105, v124, v125 offset1:1
	ds_write2_b32 v105, v126, v127 offset0:2 offset1:3
	s_mov_b32 s99, s98
	s_lshr_b32 s100, s99, 4
	s_and_b32 s99, s99, 15
	s_mul_i32 s100, s100, 0x10000
	s_mul_i32 s99, s99, 0x80
	s_add_u32 s100, s100, s99
	v_lshl_add_u64 v[116:117], s[100:101], 0, v[114:115]
	s_waitcnt lgkmcnt(0)
	s_barrier
	ds_read2_b32 v[120:121], v132 offset1:33
	ds_read2_b32 v[122:123], v132 offset0:66 offset1:99
	s_add_u32 s99, s98, 0x300
	s_min_u32 s99, s99, 0xaff
	s_lshr_b32 s100, s99, 4
	s_and_b32 s99, s99, 15
	s_mul_i32 s100, s100, 0x80
	s_mul_i32 s99, s99, 0x160000
	s_add_u32 s100, s100, s99
	v_lshl_add_u64 v[118:119], s[100:101], 0, v[110:111]
	global_load_dwordx4 v[124:127], v[118:119], off
	s_waitcnt lgkmcnt(0)
	v_cvt_pk_bf16_f32 v120, v120, v121
	v_cvt_pk_bf16_f32 v121, v122, v123
	global_store_dwordx2 v[116:117], v[120:121], off
	s_add_u32 s98, s98, 0x100
	s_cmp_lt_u32 s98, 0xb00
	s_cbranch_scc0 .Lcv_done_P15_wup
	s_waitcnt vmcnt(5)
	ds_write2_b32 v106, v128, v129 offset1:1
	ds_write2_b32 v106, v130, v131 offset0:2 offset1:3
	s_mov_b32 s99, s98
	s_lshr_b32 s100, s99, 4
	s_and_b32 s99, s99, 15
	s_mul_i32 s100, s100, 0x10000
	s_mul_i32 s99, s99, 0x80
	s_add_u32 s100, s100, s99
	v_lshl_add_u64 v[116:117], s[100:101], 0, v[114:115]
	s_waitcnt lgkmcnt(0)
	s_barrier
	ds_read2_b32 v[120:121], v133 offset1:33
	ds_read2_b32 v[122:123], v133 offset0:66 offset1:99
	s_add_u32 s99, s98, 0x300
	s_min_u32 s99, s99, 0xaff
	s_lshr_b32 s100, s99, 4
	s_and_b32 s99, s99, 15
	s_mul_i32 s100, s100, 0x80
	s_mul_i32 s99, s99, 0x160000
	s_add_u32 s100, s100, s99
	v_lshl_add_u64 v[118:119], s[100:101], 0, v[110:111]
	global_load_dwordx4 v[128:131], v[118:119], off
	s_waitcnt lgkmcnt(0)
	v_cvt_pk_bf16_f32 v120, v120, v121
	v_cvt_pk_bf16_f32 v121, v122, v123
	global_store_dwordx2 v[116:117], v[120:121], off
	s_add_u32 s98, s98, 0x100
	s_cmp_lt_u32 s98, 0xb00
	s_cbranch_scc0 .Lcv_done_P15_wup
	s_waitcnt vmcnt(5)
	ds_write2_b32 v107, v136, v137 offset1:1
	ds_write2_b32 v107, v138, v139 offset0:2 offset1:3
	s_mov_b32 s99, s98
	s_lshr_b32 s100, s99, 4
	s_and_b32 s99, s99, 15
	s_mul_i32 s100, s100, 0x10000
	s_mul_i32 s99, s99, 0x80
	s_add_u32 s100, s100, s99
	v_lshl_add_u64 v[116:117], s[100:101], 0, v[114:115]
	s_waitcnt lgkmcnt(0)
	s_barrier
	ds_read2_b32 v[120:121], v134 offset1:33
	ds_read2_b32 v[122:123], v134 offset0:66 offset1:99
	s_add_u32 s99, s98, 0x300
	s_min_u32 s99, s99, 0xaff
	s_lshr_b32 s100, s99, 4
	s_and_b32 s99, s99, 15
	s_mul_i32 s100, s100, 0x80
	s_mul_i32 s99, s99, 0x160000
	s_add_u32 s100, s100, s99
	v_lshl_add_u64 v[118:119], s[100:101], 0, v[110:111]
	global_load_dwordx4 v[136:139], v[118:119], off
	s_waitcnt lgkmcnt(0)
	v_cvt_pk_bf16_f32 v120, v120, v121
	v_cvt_pk_bf16_f32 v121, v122, v123
	global_store_dwordx2 v[116:117], v[120:121], off
	s_add_u32 s98, s98, 0x100
	s_cmp_lt_u32 s98, 0xb00
	s_cbranch_scc0 .Lcv_done_P15_wup
	s_branch .Lcv_loop_P15_wup

.Lcv_none_P15_wup:
	s_cmp_lt_u32 s82, 0x580
	s_cbranch_scc0 .Lcv_none_P15_wdn
	v_readlane_b32 s98, v254, 0
	v_readlane_b32 s99, v254, 1
	s_load_dwordx2 s[100:101], s[98:99], 0xc8
	s_load_dwordx2 s[98:99], s[98:99], 0xe0
	v_mul_u32_u24_e32 v108, 0x1000, v101
	v_lshl_add_u32 v108, v102, 2, v108
	v_mul_u32_u24_e32 v112, 0x1600, v103
	v_lshl_add_u32 v112, v104, 1, v112
	s_waitcnt lgkmcnt(0)
	v_lshl_add_u64 v[110:111], s[100:101], 0, v[108:109]
	s_add_u32 s98, s98, 0x1300000
	s_addc_u32 s99, s99, 0
	v_lshl_add_u64 v[114:115], s[98:99], 0, v[112:113]
	s_mov_b32 s101, 0
	s_mov_b32 s98, s82
	s_mov_b32 s99, s98
	s_mul_i32 s100, s99, 0x5d2
	s_lshr_b32 s100, s100, 16
	s_mul_i32 vcc_lo, s100, 44
	s_sub_u32 s99, s99, vcc_lo
	s_mul_i32 s100, s100, 0x80
	s_mul_i32 s99, s99, 0x40000
	s_add_u32 s100, s100, s99
	v_lshl_add_u64 v[118:119], s[100:101], 0, v[110:111]
	global_load_dwordx4 v[124:127], v[118:119], off
	s_add_u32 s99, s98, 0x100
	s_min_u32 s99, s99, 0x57f
	s_mul_i32 s100, s99, 0x5d2
	s_lshr_b32 s100, s100, 16
	s_mul_i32 vcc_lo, s100, 44
	s_sub_u32 s99, s99, vcc_lo
	s_mul_i32 s100, s100, 0x80
	s_mul_i32 s99, s99, 0x40000
	s_add_u32 s100, s100, s99
	v_lshl_add_u64 v[118:119], s[100:101], 0, v[110:111]
	global_load_dwordx4 v[128:131], v[118:119], off
	s_add_u32 s99, s98, 0x200
	s_min_u32 s99, s99, 0x57f
	s_mul_i32 s100, s99, 0x5d2
	s_lshr_b32 s100, s100, 16
	s_mul_i32 vcc_lo, s100, 44
	s_sub_u32 s99, s99, vcc_lo
	s_mul_i32 s100, s100, 0x80
	s_mul_i32 s99, s99, 0x40000
	s_add_u32 s100, s100, s99
	v_lshl_add_u64 v[118:119], s[100:101], 0, v[110:111]
	global_load_dwordx4 v[136:139], v[118:119], off
	s_waitcnt vmcnt(2)
	ds_write2_b32 v105, v124, v125 offset1:1
	ds_write2_b32 v105, v126, v127 offset0:2 offset1:3
	s_mov_b32 s99, s98
	s_mul_i32 s100, s99, 0x5d2
	s_lshr_b32 s100, s100, 16
	s_mul_i32 vcc_lo, s100, 44
	s_sub_u32 s99, s99, vcc_lo
	s_mul_i32 s100, s100, 0x2c000
	s_mul_i32 s99, s99, 0x80
	s_add_u32 s100, s100, s99
	v_lshl_add_u64 v[116:117], s[100:101], 0, v[114:115]
	s_waitcnt lgkmcnt(0)
	s_barrier
	ds_read2_b32 v[120:121], v132 offset1:33
	ds_read2_b32 v[122:123], v132 offset0:66 offset1:99
	s_add_u32 s99, s98, 0x300
	s_min_u32 s99, s99, 0x57f
	s_mul_i32 s100, s99, 0x5d2
	s_lshr_b32 s100, s100, 16
	s_mul_i32 vcc_lo, s100, 44
	s_sub_u32 s99, s99, vcc_lo
	s_mul_i32 s100, s100, 0x80
	s_mul_i32 s99, s99, 0x40000
	s_add_u32 s100, s100, s99
	v_lshl_add_u64 v[118:119], s[100:101], 0, v[110:111]
	global_load_dwordx4 v[124:127], v[118:119], off
	s_waitcnt lgkmcnt(0)
	v_cvt_pk_bf16_f32 v120, v120, v121
	v_cvt_pk_bf16_f32 v121, v122, v123
	global_store_dwordx2 v[116:117], v[120:121], off
	s_add_u32 s98, s98, 0x100
	s_cmp_lt_u32 s98, 0x580
	s_cbranch_scc0 .Lcv_done_P15_wdn
	s_waitcnt vmcnt(3)
	ds_write2_b32 v106, v128, v129 offset1:1
	ds_write2_b32 v106, v130, v131 offset0:2 offset1:3
	s_mov_b32 s99, s98
	s_mul_i32 s100, s99, 0x5d2
	s_lshr_b32 s100, s100, 16
	s_mul_i32 vcc_lo, s100, 44
	s_sub_u32 s99, s99, vcc_lo
	s_mul_i32 s100, s100, 0x2c000
	s_mul_i32 s99, s99, 0x80
	s_add_u32 s100, s100, s99
	v_lshl_add_u64 v[116:117], s[100:101], 0, v[114:115]
	s_waitcnt lgkmcnt(0)
	s_barrier
	ds_read2_b32 v[120:121], v133 offset1:33
	ds_read2_b32 v[122:123], v133 offset0:66 offset1:99
	s_add_u32 s99, s98, 0x300
	s_min_u32 s99, s99, 0x57f
	s_mul_i32 s100, s99, 0x5d2
	s_lshr_b32 s100, s100, 16
	s_mul_i32 vcc_lo, s100, 44
	s_sub_u32 s99, s99, vcc_lo
	s_mul_i32 s100, s100, 0x80
	s_mul_i32 s99, s99, 0x40000
	s_add_u32 s100, s100, s99
	v_lshl_add_u64 v[118:119], s[100:101], 0, v[110:111]
	global_load_dwordx4 v[128:131], v[118:119], off
	s_waitcnt lgkmcnt(0)
	v_cvt_pk_bf16_f32 v120, v120, v121
	v_cvt_pk_bf16_f32 v121, v122, v123
	global_store_dwordx2 v[116:117], v[120:121], off
	s_add_u32 s98, s98, 0x100
	s_cmp_lt_u32 s98, 0x580
	s_cbranch_scc0 .Lcv_done_P15_wdn
	s_waitcnt vmcnt(4)
	ds_write2_b32 v107, v136, v137 offset1:1
	ds_write2_b32 v107, v138, v139 offset0:2 offset1:3
	s_mov_b32 s99, s98
	s_mul_i32 s100, s99, 0x5d2
	s_lshr_b32 s100, s100, 16
	s_mul_i32 vcc_lo, s100, 44
	s_sub_u32 s99, s99, vcc_lo
	s_mul_i32 s100, s100, 0x2c000
	s_mul_i32 s99, s99, 0x80
	s_add_u32 s100, s100, s99
	v_lshl_add_u64 v[116:117], s[100:101], 0, v[114:115]
	s_waitcnt lgkmcnt(0)
	s_barrier
	ds_read2_b32 v[120:121], v134 offset1:33
	ds_read2_b32 v[122:123], v134 offset0:66 offset1:99
	s_add_u32 s99, s98, 0x300
	s_min_u32 s99, s99, 0x57f
	s_mul_i32 s100, s99, 0x5d2
	s_lshr_b32 s100, s100, 16
	s_mul_i32 vcc_lo, s100, 44
	s_sub_u32 s99, s99, vcc_lo
	s_mul_i32 s100, s100, 0x80
	s_mul_i32 s99, s99, 0x40000
	s_add_u32 s100, s100, s99
	v_lshl_add_u64 v[118:119], s[100:101], 0, v[110:111]
	global_load_dwordx4 v[136:139], v[118:119], off
	s_waitcnt lgkmcnt(0)
	v_cvt_pk_bf16_f32 v120, v120, v121
	v_cvt_pk_bf16_f32 v121, v122, v123
	global_store_dwordx2 v[116:117], v[120:121], off
	s_add_u32 s98, s98, 0x100
	s_cmp_lt_u32 s98, 0x580
	s_cbranch_scc0 .Lcv_done_P15_wdn
.Lcv_loop_P15_wdn:
	s_waitcnt vmcnt(5)
	ds_write2_b32 v105, v124, v125 offset1:1
	ds_write2_b32 v105, v126, v127 offset0:2 offset1:3
	s_mov_b32 s99, s98
	s_mul_i32 s100, s99, 0x5d2
	s_lshr_b32 s100, s100, 16
	s_mul_i32 vcc_lo, s100, 44
	s_sub_u32 s99, s99, vcc_lo
	s_mul_i32 s100, s100, 0x2c000
	s_mul_i32 s99, s99, 0x80
	s_add_u32 s100, s100, s99
	v_lshl_add_u64 v[116:117], s[100:101], 0, v[114:115]
	s_waitcnt lgkmcnt(0)
	s_barrier
	ds_read2_b32 v[120:121], v132 offset1:33
	ds_read2_b32 v[122:123], v132 offset0:66 offset1:99
	s_add_u32 s99, s98, 0x300
	s_min_u32 s99, s99, 0x57f
	s_mul_i32 s100, s99, 0x5d2
	s_lshr_b32 s100, s100, 16
	s_mul_i32 vcc_lo, s100, 44
	s_sub_u32 s99, s99, vcc_lo
	s_mul_i32 s100, s100, 0x80
	s_mul_i32 s99, s99, 0x40000
	s_add_u32 s100, s100, s99
	v_lshl_add_u64 v[118:119], s[100:101], 0, v[110:111]
	global_load_dwordx4 v[124:127], v[118:119], off
	s_waitcnt lgkmcnt(0)
	v_cvt_pk_bf16_f32 v120, v120, v121
	v_cvt_pk_bf16_f32 v121, v122, v123
	global_store_dwordx2 v[116:117], v[120:121], off
	s_add_u32 s98, s98, 0x100
	s_cmp_lt_u32 s98, 0x580
	s_cbranch_scc0 .Lcv_done_P15_wdn
	s_waitcnt vmcnt(5)
	ds_write2_b32 v106, v128, v129 offset1:1
	ds_write2_b32 v106, v130, v131 offset0:2 offset1:3
	s_mov_b32 s99, s98
	s_mul_i32 s100, s99, 0x5d2
	s_lshr_b32 s100, s100, 16
	s_mul_i32 vcc_lo, s100, 44
	s_sub_u32 s99, s99, vcc_lo
	s_mul_i32 s100, s100, 0x2c000
	s_mul_i32 s99, s99, 0x80
	s_add_u32 s100, s100, s99
	v_lshl_add_u64 v[116:117], s[100:101], 0, v[114:115]
	s_waitcnt lgkmcnt(0)
	s_barrier
	ds_read2_b32 v[120:121], v133 offset1:33
	ds_read2_b32 v[122:123], v133 offset0:66 offset1:99
	s_add_u32 s99, s98, 0x300
	s_min_u32 s99, s99, 0x57f
	s_mul_i32 s100, s99, 0x5d2
	s_lshr_b32 s100, s100, 16
	s_mul_i32 vcc_lo, s100, 44
	s_sub_u32 s99, s99, vcc_lo
	s_mul_i32 s100, s100, 0x80
	s_mul_i32 s99, s99, 0x40000
	s_add_u32 s100, s100, s99
	v_lshl_add_u64 v[118:119], s[100:101], 0, v[110:111]
	global_load_dwordx4 v[128:131], v[118:119], off
	s_waitcnt lgkmcnt(0)
	v_cvt_pk_bf16_f32 v120, v120, v121
	v_cvt_pk_bf16_f32 v121, v122, v123
	global_store_dwordx2 v[116:117], v[120:121], off
	s_add_u32 s98, s98, 0x100
	s_cmp_lt_u32 s98, 0x580
	s_cbranch_scc0 .Lcv_done_P15_wdn
	s_waitcnt vmcnt(5)
	ds_write2_b32 v107, v136, v137 offset1:1
	ds_write2_b32 v107, v138, v139 offset0:2 offset1:3
	s_mov_b32 s99, s98
	s_mul_i32 s100, s99, 0x5d2
	s_lshr_b32 s100, s100, 16
	s_mul_i32 vcc_lo, s100, 44
	s_sub_u32 s99, s99, vcc_lo
	s_mul_i32 s100, s100, 0x2c000
	s_mul_i32 s99, s99, 0x80
	s_add_u32 s100, s100, s99
	v_lshl_add_u64 v[116:117], s[100:101], 0, v[114:115]
	s_waitcnt lgkmcnt(0)
	s_barrier
	ds_read2_b32 v[120:121], v134 offset1:33
	ds_read2_b32 v[122:123], v134 offset0:66 offset1:99
	s_add_u32 s99, s98, 0x300
	s_min_u32 s99, s99, 0x57f
	s_mul_i32 s100, s99, 0x5d2
	s_lshr_b32 s100, s100, 16
	s_mul_i32 vcc_lo, s100, 44
	s_sub_u32 s99, s99, vcc_lo
	s_mul_i32 s100, s100, 0x80
	s_mul_i32 s99, s99, 0x40000
	s_add_u32 s100, s100, s99
	v_lshl_add_u64 v[118:119], s[100:101], 0, v[110:111]
	global_load_dwordx4 v[136:139], v[118:119], off
	s_waitcnt lgkmcnt(0)
	v_cvt_pk_bf16_f32 v120, v120, v121
	v_cvt_pk_bf16_f32 v121, v122, v123
	global_store_dwordx2 v[116:117], v[120:121], off
	s_add_u32 s98, s98, 0x100
	s_cmp_lt_u32 s98, 0x580
	s_cbranch_scc0 .Lcv_done_P15_wdn
	s_branch .Lcv_loop_P15_wdn

.Lcv_skip_P15:
	v_readlane_b32 s4, v254, 0
	v_readlane_b32 s5, v254, 1
	s_load_dwordx2 s[0:1], s[4:5], 0xe0
	s_cmpk_gt_i32 s82, 0xaff
	v_readlane_b32 s8, v254, 2
	s_waitcnt vmcnt(0)
	v_mbcnt_lo_u32_b32 v0, -1, 0
	v_mbcnt_hi_u32_b32 v0, -1, v0
	s_cbranch_scc1 .LBB0_1257
	v_readlane_b32 s98, v254, 5
	s_nop 0
	s_cmpk_eq_i32 s98, 0x100
	s_cbranch_scc1 .LBB0_1257
	s_load_dwordx2 s[2:3], s[4:5], 0xb0
	s_waitcnt lgkmcnt(0)
	s_add_u32 s6, s0, 0x800000
	v_lshl_add_u32 v1, s8, 6, v0
	v_readlane_b32 s8, v254, 50
	s_addc_u32 s7, s1, 0
	s_lshr_b32 s8, s8, 28
	s_add_i32 s10, s82, s8
	s_lshl_b32 s8, s10, 1
	s_and_b32 s10, s10, 0x3fffff0
	v_ashrrev_i32_e32 v10, 3, v1
	s_sub_i32 s10, s82, s10
	s_andn2_b32 s8, s8, 31
	v_lshlrev_b32_e32 v11, 2, v1
	v_lshl_add_u32 v4, s10, 6, v10
	s_movk_i32 s10, 0x5800
	v_mov_b64_e32 v[2:3], s[2:3]
	s_ashr_i32 s9, s8, 31
	v_and_b32_e32 v0, 28, v11
	v_mad_i64_i32 v[2:3], s[12:13], v4, s10, v[2:3]
	v_lshl_add_u64 v[2:3], s[8:9], 2, v[2:3]
	v_mov_b32_e32 v9, 0
	v_lshlrev_b32_e32 v8, 2, v0
	v_lshl_add_u64 v[2:3], v[2:3], 0, v[8:9]
	global_load_dwordx4 v[4:7], v[2:3], off
	s_movk_i32 s8, 0x84
	v_and_b32_e32 v2, 60, v11
	v_ashrrev_i32_e32 v12, 4, v1
	v_mul_lo_u32 v3, v10, s8
	v_readlane_b32 s8, v254, 5
	v_add_u32_e32 v1, 0, v8
	v_mul_u32_u24_e32 v8, 0x84, v2
	v_lshlrev_b32_e32 v11, 2, v12
	s_lshl_b32 s12, s8, 6
	v_add3_u32 v13, 0, v8, v11
	v_add_u32_e32 v14, s12, v10
	v_lshlrev_b32_e32 v8, 2, v0
	v_add_u32_e32 v15, v1, v3
	v_lshlrev_b32_e32 v10, 1, v2
	s_lshl_b32 s11, s82, 6
	v_mov_b32_e32 v11, v9
	s_mov_b32 s14, s82
	v_readlane_b32 s9, v254, 6
	s_waitcnt vmcnt(0)
	v_mov_b64_e32 v[0:1], v[4:5]
	v_mov_b64_e32 v[2:3], v[6:7]
	s_branch .LBB0_1255

.LBB0_1257:
	s_cmpk_gt_i32 s82, 0x57f
	v_readlane_b32 s6, v254, 2
	v_mbcnt_lo_u32_b32 v0, -1, 0
	v_mbcnt_hi_u32_b32 v0, -1, v0
	s_cbranch_scc1 .LBB0_1262
	v_readlane_b32 s98, v254, 5
	s_nop 0
	s_cmpk_eq_i32 s98, 0x100
	s_cbranch_scc1 .LBB0_1262
	s_waitcnt lgkmcnt(0)
	s_add_u32 s12, s0, 0x1300000
	v_lshl_add_u32 v5, s6, 6, v0
	s_mul_hi_i32 s6, s82, 0x2e8ba2e9
	s_addc_u32 s13, s1, 0
	s_lshr_b32 s7, s6, 31
	s_ashr_i32 s6, s6, 3
	s_add_i32 s6, s6, s7
	s_load_dwordx2 s[2:3], s[4:5], 0xc8
	s_mul_i32 s7, s6, 44
	v_ashrrev_i32_e32 v7, 3, v5
	s_sub_i32 s8, s82, s7
	v_lshl_add_u32 v0, s8, 6, v7
	v_ashrrev_i32_e32 v1, 31, v0
	s_lshl_b32 s6, s6, 5
	v_lshlrev_b32_e32 v6, 2, v5
	v_lshlrev_b64 v[0:1], 12, v[0:1]
	s_ashr_i32 s7, s6, 31
	v_and_b32_e32 v4, 28, v6
	s_waitcnt lgkmcnt(0)
	v_lshl_add_u64 v[0:1], s[2:3], 0, v[0:1]
	v_lshl_add_u64 v[0:1], s[6:7], 2, v[0:1]
	v_mov_b32_e32 v9, 0
	v_lshlrev_b32_e32 v8, 2, v4
	v_lshl_add_u64 v[0:1], v[0:1], 0, v[8:9]
	global_load_dwordx4 v[0:3], v[0:1], off
	s_movk_i32 s6, 0x84
	v_and_b32_e32 v6, 60, v6
	v_ashrrev_i32_e32 v14, 4, v5
	v_mul_lo_u32 v10, v7, s6
	v_readlane_b32 s6, v254, 5
	v_add_u32_e32 v5, 0, v8
	v_mul_u32_u24_e32 v8, 0x84, v6
	v_lshlrev_b32_e32 v11, 2, v14
	s_lshl_b32 s9, s6, 6
	v_add3_u32 v15, 0, v8, v11
	v_add_u32_e32 v16, s9, v7
	v_lshlrev_b32_e32 v8, 2, v4
	v_add_u32_e32 v17, v5, v10
	v_lshlrev_b32_e32 v12, 1, v6
	s_lshl_b32 s8, s82, 6
	s_movk_i32 s10, 0x1600
	v_mov_b64_e32 v[10:11], s[12:13]
	v_mov_b32_e32 v13, v9
	s_mov_b32 s12, s82
	v_readlane_b32 s7, v254, 6
	s_waitcnt vmcnt(0)
	v_mov_b64_e32 v[6:7], v[2:3]
	v_mov_b64_e32 v[4:5], v[0:1]
	s_branch .LBB0_1260
